# K-loop: plus ds_reads issued before glds address SALU in each load segment (b,c,d)
# baseline (speedup 1.0000x reference)
; #define PG8_STAGE(bufoff, gbase, voff) do { _Pragma("unroll") for (int _i = 0; _i < 2; ++_i) \
;         __builtin_amdgcn_global_load_lds((const unsigned*)((const char*)(gbase) + (voff)[_i]), (LAS unsigned*)(lds + (bufoff) + ldsw + _i * 8192), 16, 0, 0); } while (0)
; #define PG8_LDA(dst, b, h) do { _Pragma("unroll") for (int m = 0; m < 4; ++m) _Pragma("unroll") for (int k = 0; k < 2; ++k) dst[m][k] = *(const LAS bf16x8*)(lds + PG8_SA(b, h) + aoff + m * 2048 + k * 1024); } while (0)
; #define PG8_LDB(dst, b, h) do { _Pragma("unroll") for (int n = 0; n < 2; ++n) _Pragma("unroll") for (int k = 0; k < 2; ++k) dst[n][k] = *(const LAS bf16x8*)(lds + PG8_SB(b, h) + boff + n * 2048 + k * 1024); } while (0)
; #define PG8_MMA(ai, bj, At, Bt) do { __builtin_amdgcn_s_setprio(1); _Pragma("unroll") for (int m = 0; m < 4; ++m) _Pragma("unroll") for (int n = 0; n < 2; ++n) _Pragma("unroll") for (int k = 0; k < 2; ++k) \
;         acc[ai][bj][m][n] = __builtin_amdgcn_mfma_f32_16x16x32_bf16(Bt[n][k], At[m][k], acc[ai][bj][m][n], 0, 0, 0); __builtin_amdgcn_s_setprio(0); } while (0)
; #define PG8_WAIT_L(n) asm volatile("s_waitcnt lgkmcnt(" #n ")" ::: "memory")
; #define PG8_BAR __builtin_amdgcn_s_barrier()
; #define PG8_SCHED __builtin_amdgcn_sched_barrier(0)
; template <class Epi>
; __device__ __forceinline__ void gemm_phase(LAS unsigned char* lds, const Gemm g, const StaticOrder& S, const Epi& E) {
;     ...
;             const bool last = (t == nt - 2);
;             const char* a1 = cA + (size_t)(t + 1) * kstep;
;             const char* a2 = last ? nA : cA + (size_t)(t + 2) * kstep; const char* b2 = last ? nB : cB + (size_t)(t + 2) * kstep;
;             const char* a3 = a2 + kstep; const char* b3 = b2 + kstep;
;             PG8_LDB(B0, 0, 0); PG8_SCHED; PG8_LDA(At, 0, 0); PG8_STAGE(PG8_SA(1, 1), a1 + hstepA, voffA);
;             PG8_WAIT_L(8); PG8_BAR; PG8_WAIT_L(0); PG8_MMA(0, 0, At, B0); PG8_BAR; PG8_SCHED;
;             PG8_LDB(B1, 0, 1); PG8_STAGE(PG8_SB(0, 0), b2, voffB);
;             PG8_BAR; PG8_WAIT_L(0); PG8_MMA(0, 1, At, B1); PG8_BAR;
;             PG8_LDA(At, 0, 1); PG8_STAGE(PG8_SA(0, 0), a2, voffA);
;             PG8_BAR; PG8_WAIT_L(0); PG8_MMA(1, 0, At, B0); PG8_BAR; PG8_SCHED;
.LBB0_141:
	s_mov_b32 s55, 0x10000
	v_add_u32_e32 v148, s55, v134
	ds_read_b128 v[136:139], v148
	ds_read_b128 v[140:143], v148 offset:1024
	ds_read_b128 v[144:147], v148 offset:2048
	ds_read_b128 v[148:151], v148 offset:3072
	ds_read_b128 v[156:159], v135
	ds_read_b128 v[160:163], v135 offset:1024
	ds_read_b128 v[164:167], v135 offset:2048
	ds_read_b128 v[168:171], v135 offset:3072
	ds_read_b128 v[172:175], v135 offset:4096
	ds_read_b128 v[176:179], v135 offset:5120
	ds_read_b128 v[180:183], v135 offset:6144
	ds_read_b128 v[184:187], v135 offset:7168
	s_add_u32 s24, s22, 0xfff84000
	s_addc_u32 s25, s23, -1
	s_cmp_eq_u32 s54, 28
	s_cselect_b32 s28, s49, s24
	s_cselect_b32 s29, s15, s25
	s_cselect_b32 s24, s50, s51
	s_cselect_b32 s25, s5, s52
	s_add_u32 s26, s28, 0x4000
	s_addc_u32 s27, s29, 0
	s_add_i32 m0, s37, 0xc000
	v_lshl_add_u64 v[188:189], s[22:23], 0, v[128:129]
	global_load_lds_dwordx4 v[188:189], off
	s_add_i32 m0, s37, 0xe000
	v_lshl_add_u64 v[188:189], s[22:23], 0, v[130:131]
	global_load_lds_dwordx4 v[188:189], off
	s_waitcnt lgkmcnt(8)
	s_barrier
	s_waitcnt lgkmcnt(0)
	s_setprio 1
	v_mfma_f32_16x16x32_bf16 v[124:127], v[136:139], v[156:159], v[124:127]
	v_mfma_f32_16x16x32_bf16 v[120:123], v[144:147], v[156:159], v[120:123]
	v_mfma_f32_16x16x32_bf16 v[108:111], v[136:139], v[164:167], v[108:111]
	v_mfma_f32_16x16x32_bf16 v[104:107], v[144:147], v[164:167], v[104:107]
	v_mfma_f32_16x16x32_bf16 v[92:95], v[136:139], v[172:175], v[92:95]
	v_mfma_f32_16x16x32_bf16 v[88:91], v[144:147], v[172:175], v[88:91]
	v_mfma_f32_16x16x32_bf16 v[76:79], v[136:139], v[180:183], v[76:79]
	v_mfma_f32_16x16x32_bf16 v[72:75], v[144:147], v[180:183], v[72:75]
	v_mfma_f32_16x16x32_bf16 v[124:127], v[140:143], v[160:163], v[124:127]
	v_mfma_f32_16x16x32_bf16 v[120:123], v[148:151], v[160:163], v[120:123]
	v_mfma_f32_16x16x32_bf16 v[108:111], v[140:143], v[168:171], v[108:111]
	v_mfma_f32_16x16x32_bf16 v[104:107], v[148:151], v[168:171], v[104:107]
	v_mfma_f32_16x16x32_bf16 v[92:95], v[140:143], v[176:179], v[92:95]
	v_mfma_f32_16x16x32_bf16 v[88:91], v[148:151], v[176:179], v[88:91]
	v_mfma_f32_16x16x32_bf16 v[76:79], v[140:143], v[184:187], v[76:79]
	s_setprio 0
	v_mfma_f32_16x16x32_bf16 v[72:75], v[148:151], v[184:187], v[72:75]
	s_barrier
	s_mov_b32 s58, 0x14000
	v_add_u32_e32 v152, s58, v134
	ds_read_b128 v[188:191], v152
	ds_read_b128 v[192:195], v152 offset:1024
	ds_read_b128 v[196:199], v152 offset:2048
	ds_read_b128 v[200:203], v152 offset:3072
	s_add_i32 s55, s55, s36
	s_mov_b32 m0, s55
	v_lshl_add_u64 v[204:205], s[24:25], 0, v[128:129]
	global_load_lds_dwordx4 v[204:205], off
	s_add_i32 m0, s55, 0x2000
	v_lshl_add_u64 v[204:205], s[24:25], 0, v[130:131]
	global_load_lds_dwordx4 v[204:205], off
	s_barrier
	s_waitcnt lgkmcnt(0)
	s_setprio 1
	v_mfma_f32_16x16x32_bf16 v[116:119], v[188:191], v[156:159], v[116:119]
	v_mfma_f32_16x16x32_bf16 v[112:115], v[196:199], v[156:159], v[112:115]
	s_mov_b32 m0, s37
	v_lshl_add_u64 v[204:205], s[28:29], 0, v[128:129]
	v_mfma_f32_16x16x32_bf16 v[100:103], v[188:191], v[164:167], v[100:103]
	v_mfma_f32_16x16x32_bf16 v[96:99], v[196:199], v[164:167], v[96:99]
	v_mfma_f32_16x16x32_bf16 v[84:87], v[188:191], v[172:175], v[84:87]
	v_mfma_f32_16x16x32_bf16 v[80:83], v[196:199], v[172:175], v[80:83]
	v_mfma_f32_16x16x32_bf16 v[68:71], v[188:191], v[180:183], v[68:71]
	v_mfma_f32_16x16x32_bf16 v[64:67], v[196:199], v[180:183], v[64:67]
	v_mfma_f32_16x16x32_bf16 v[116:119], v[192:195], v[160:163], v[116:119]
	v_mfma_f32_16x16x32_bf16 v[112:115], v[200:203], v[160:163], v[112:115]
	v_mfma_f32_16x16x32_bf16 v[100:103], v[192:195], v[168:171], v[100:103]
	v_mfma_f32_16x16x32_bf16 v[96:99], v[200:203], v[168:171], v[96:99]
	v_mfma_f32_16x16x32_bf16 v[84:87], v[192:195], v[176:179], v[84:87]
	v_mfma_f32_16x16x32_bf16 v[80:83], v[200:203], v[176:179], v[80:83]
	v_mfma_f32_16x16x32_bf16 v[68:71], v[192:195], v[184:187], v[68:71]
	s_setprio 0
	v_mfma_f32_16x16x32_bf16 v[64:67], v[200:203], v[184:187], v[64:67]
	s_barrier
	ds_read_b128 v[156:159], v135 offset:16384
	ds_read_b128 v[160:163], v135 offset:17408
	ds_read_b128 v[164:167], v135 offset:18432
	ds_read_b128 v[168:171], v135 offset:19456
	ds_read_b128 v[172:175], v135 offset:20480
	ds_read_b128 v[176:179], v135 offset:21504
	ds_read_b128 v[180:183], v135 offset:22528
	ds_read_b128 v[184:187], v135 offset:23552
	global_load_lds_dwordx4 v[204:205], off
	s_mov_b32 m0, s38
	v_lshl_add_u64 v[204:205], s[28:29], 0, v[130:131]
	global_load_lds_dwordx4 v[204:205], off
	s_barrier
	s_waitcnt lgkmcnt(0)
	s_setprio 1
	v_mfma_f32_16x16x32_bf16 v[60:63], v[136:139], v[156:159], v[60:63]
	v_mfma_f32_16x16x32_bf16 v[56:59], v[144:147], v[156:159], v[56:59]
	v_mfma_f32_16x16x32_bf16 v[44:47], v[136:139], v[164:167], v[44:47]
	v_mfma_f32_16x16x32_bf16 v[40:43], v[144:147], v[164:167], v[40:43]
	v_mfma_f32_16x16x32_bf16 v[28:31], v[136:139], v[172:175], v[28:31]
	v_mfma_f32_16x16x32_bf16 v[24:27], v[144:147], v[172:175], v[24:27]
	v_mfma_f32_16x16x32_bf16 v[12:15], v[136:139], v[180:183], v[12:15]
	v_mfma_f32_16x16x32_bf16 v[8:11], v[144:147], v[180:183], v[8:11]
	v_mfma_f32_16x16x32_bf16 v[60:63], v[140:143], v[160:163], v[60:63]
	v_mfma_f32_16x16x32_bf16 v[56:59], v[148:151], v[160:163], v[56:59]
	v_mfma_f32_16x16x32_bf16 v[44:47], v[140:143], v[168:171], v[44:47]
	v_mfma_f32_16x16x32_bf16 v[40:43], v[148:151], v[168:171], v[40:43]
	v_mfma_f32_16x16x32_bf16 v[28:31], v[140:143], v[176:179], v[28:31]
	v_mfma_f32_16x16x32_bf16 v[24:27], v[148:151], v[176:179], v[24:27]
	v_mfma_f32_16x16x32_bf16 v[12:15], v[140:143], v[184:187], v[12:15]
	s_setprio 0
	v_mfma_f32_16x16x32_bf16 v[8:11], v[148:151], v[184:187], v[8:11]
	s_barrier
; #define PG8_STAGE(bufoff, gbase, voff) do { _Pragma("unroll") for (int _i = 0; _i < 2; ++_i) \
;         __builtin_amdgcn_global_load_lds((const unsigned*)((const char*)(gbase) + (voff)[_i]), (LAS unsigned*)(lds + (bufoff) + ldsw + _i * 8192), 16, 0, 0); } while (0)
; #define PG8_LDA(dst, b, h) do { _Pragma("unroll") for (int m = 0; m < 4; ++m) _Pragma("unroll") for (int k = 0; k < 2; ++k) dst[m][k] = *(const LAS bf16x8*)(lds + PG8_SA(b, h) + aoff + m * 2048 + k * 1024); } while (0)
; #define PG8_LDB(dst, b, h) do { _Pragma("unroll") for (int n = 0; n < 2; ++n) _Pragma("unroll") for (int k = 0; k < 2; ++k) dst[n][k] = *(const LAS bf16x8*)(lds + PG8_SB(b, h) + boff + n * 2048 + k * 1024); } while (0)
; #define PG8_MMA(ai, bj, At, Bt) do { __builtin_amdgcn_s_setprio(1); _Pragma("unroll") for (int m = 0; m < 4; ++m) _Pragma("unroll") for (int n = 0; n < 2; ++n) _Pragma("unroll") for (int k = 0; k < 2; ++k) \
;         acc[ai][bj][m][n] = __builtin_amdgcn_mfma_f32_16x16x32_bf16(Bt[n][k], At[m][k], acc[ai][bj][m][n], 0, 0, 0); __builtin_amdgcn_s_setprio(0); } while (0)
; #define PG8_WAIT_V(n) asm volatile("s_waitcnt vmcnt(" #n ")" ::: "memory")
; #define PG8_WAIT_L(n) asm volatile("s_waitcnt lgkmcnt(" #n ")" ::: "memory")
; #define PG8_BAR __builtin_amdgcn_s_barrier()
; #define PG8_SCHED __builtin_amdgcn_sched_barrier(0)
; template <class Epi>
; __device__ __forceinline__ void gemm_phase(LAS unsigned char* lds, const Gemm g, const StaticOrder& S, const Epi& E) {
;     ...
;             PG8_STAGE(PG8_SB(0, 1), b2 + hstepB, voffB);
;             PG8_WAIT_V(6); PG8_BAR; PG8_MMA(1, 1, At, B1); PG8_BAR;
;             PG8_LDB(B0, 1, 0); PG8_SCHED; PG8_LDA(At, 1, 0); PG8_STAGE(PG8_SA(0, 1), a2 + hstepA, voffA);
;             PG8_WAIT_L(8); PG8_BAR; PG8_WAIT_L(0); PG8_MMA(0, 0, At, B0); PG8_BAR; PG8_SCHED;
;             PG8_LDB(B1, 1, 1); PG8_STAGE(PG8_SB(1, 0), b3, voffB);
;             PG8_BAR; PG8_WAIT_L(0); PG8_MMA(0, 1, At, B1); PG8_BAR;
;             PG8_LDA(At, 1, 1); PG8_STAGE(PG8_SA(1, 0), a3, voffA);
;             PG8_BAR; PG8_WAIT_L(0); PG8_MMA(1, 0, At, B0); PG8_BAR; PG8_SCHED;
	s_add_u32 s56, s24, 0x80000
	s_addc_u32 s57, s25, 0
	s_add_i32 s55, s58, s36
	s_mov_b32 m0, s55
	v_lshl_add_u64 v[136:137], s[56:57], 0, v[128:129]
	global_load_lds_dwordx4 v[136:137], off
	s_add_i32 m0, s55, 0x2000
	v_lshl_add_u64 v[136:137], s[56:57], 0, v[130:131]
	global_load_lds_dwordx4 v[136:137], off
	s_waitcnt vmcnt(6)
	s_barrier
	s_setprio 1
	v_mfma_f32_16x16x32_bf16 v[52:55], v[188:191], v[156:159], v[52:55]
	v_mfma_f32_16x16x32_bf16 v[48:51], v[196:199], v[156:159], v[48:51]
	s_add_i32 s55, 0, 0x18000
	v_add_u32_e32 v148, s55, v134
	v_mfma_f32_16x16x32_bf16 v[36:39], v[188:191], v[164:167], v[36:39]
	v_mfma_f32_16x16x32_bf16 v[32:35], v[196:199], v[164:167], v[32:35]
	v_mfma_f32_16x16x32_bf16 v[20:23], v[188:191], v[172:175], v[20:23]
	v_mfma_f32_16x16x32_bf16 v[16:19], v[196:199], v[172:175], v[16:19]
	v_mfma_f32_16x16x32_bf16 v[4:7], v[188:191], v[180:183], v[4:7]
	v_mfma_f32_16x16x32_bf16 v[0:3], v[196:199], v[180:183], v[0:3]
	v_mfma_f32_16x16x32_bf16 v[52:55], v[192:195], v[160:163], v[52:55]
	v_mfma_f32_16x16x32_bf16 v[48:51], v[200:203], v[160:163], v[48:51]
	v_mfma_f32_16x16x32_bf16 v[36:39], v[192:195], v[168:171], v[36:39]
	v_mfma_f32_16x16x32_bf16 v[32:35], v[200:203], v[168:171], v[32:35]
	v_mfma_f32_16x16x32_bf16 v[20:23], v[192:195], v[176:179], v[20:23]
	v_mfma_f32_16x16x32_bf16 v[16:19], v[200:203], v[176:179], v[16:19]
	v_mfma_f32_16x16x32_bf16 v[4:7], v[192:195], v[184:187], v[4:7]
	s_setprio 0
	v_mfma_f32_16x16x32_bf16 v[0:3], v[200:203], v[184:187], v[0:3]
	s_barrier
	ds_read_b128 v[136:139], v148
	ds_read_b128 v[140:143], v148 offset:1024
	ds_read_b128 v[144:147], v148 offset:2048
	ds_read_b128 v[148:151], v148 offset:3072
	ds_read_b128 v[156:159], v135 offset:32768
	ds_read_b128 v[160:163], v135 offset:33792
	ds_read_b128 v[164:167], v135 offset:34816
	ds_read_b128 v[168:171], v135 offset:35840
	ds_read_b128 v[172:175], v135 offset:36864
	ds_read_b128 v[176:179], v135 offset:37888
	ds_read_b128 v[180:183], v135 offset:38912
	ds_read_b128 v[184:187], v135 offset:39936
	s_add_u32 s28, s28, 0x80000
	s_addc_u32 s29, s29, 0
	s_mov_b32 m0, s39
	v_lshl_add_u64 v[188:189], s[28:29], 0, v[128:129]
	global_load_lds_dwordx4 v[188:189], off
	s_mov_b32 m0, s40
	v_lshl_add_u64 v[188:189], s[28:29], 0, v[130:131]
	global_load_lds_dwordx4 v[188:189], off
	s_waitcnt lgkmcnt(8)
	s_barrier
	s_waitcnt lgkmcnt(0)
	s_setprio 1
	v_mfma_f32_16x16x32_bf16 v[124:127], v[136:139], v[156:159], v[124:127]
	v_mfma_f32_16x16x32_bf16 v[120:123], v[144:147], v[156:159], v[120:123]
	v_mfma_f32_16x16x32_bf16 v[108:111], v[136:139], v[164:167], v[108:111]
	v_mfma_f32_16x16x32_bf16 v[104:107], v[144:147], v[164:167], v[104:107]
	v_mfma_f32_16x16x32_bf16 v[92:95], v[136:139], v[172:175], v[92:95]
	v_mfma_f32_16x16x32_bf16 v[88:91], v[144:147], v[172:175], v[88:91]
	v_mfma_f32_16x16x32_bf16 v[76:79], v[136:139], v[180:183], v[76:79]
	v_mfma_f32_16x16x32_bf16 v[72:75], v[144:147], v[180:183], v[72:75]
	v_mfma_f32_16x16x32_bf16 v[124:127], v[140:143], v[160:163], v[124:127]
	v_mfma_f32_16x16x32_bf16 v[120:123], v[148:151], v[160:163], v[120:123]
	v_mfma_f32_16x16x32_bf16 v[108:111], v[140:143], v[168:171], v[108:111]
	v_mfma_f32_16x16x32_bf16 v[104:107], v[148:151], v[168:171], v[104:107]
	v_mfma_f32_16x16x32_bf16 v[92:95], v[140:143], v[176:179], v[92:95]
	v_mfma_f32_16x16x32_bf16 v[88:91], v[148:151], v[176:179], v[88:91]
	v_mfma_f32_16x16x32_bf16 v[76:79], v[140:143], v[184:187], v[76:79]
	s_setprio 0
	v_mfma_f32_16x16x32_bf16 v[72:75], v[148:151], v[184:187], v[72:75]
	s_barrier
	s_mov_b32 s56, 0x1c000
	v_add_u32_e32 v152, s56, v134
	ds_read_b128 v[188:191], v152
	ds_read_b128 v[192:195], v152 offset:1024
	ds_read_b128 v[196:199], v152 offset:2048
	ds_read_b128 v[200:203], v152 offset:3072
	s_add_u32 s28, s24, 0x4000
	s_addc_u32 s29, s25, 0
	s_add_i32 s55, s55, s36
	s_mov_b32 m0, s55
	v_lshl_add_u64 v[204:205], s[28:29], 0, v[128:129]
	global_load_lds_dwordx4 v[204:205], off
	s_add_i32 m0, s55, 0x2000
	v_lshl_add_u64 v[204:205], s[28:29], 0, v[130:131]
	global_load_lds_dwordx4 v[204:205], off
	s_barrier
	s_waitcnt lgkmcnt(0)
	s_setprio 1
	v_mfma_f32_16x16x32_bf16 v[116:119], v[188:191], v[156:159], v[116:119]
	v_mfma_f32_16x16x32_bf16 v[112:115], v[196:199], v[156:159], v[112:115]
	s_mov_b32 m0, s43
	v_lshl_add_u64 v[204:205], s[26:27], 0, v[128:129]
	v_mfma_f32_16x16x32_bf16 v[100:103], v[188:191], v[164:167], v[100:103]
	v_mfma_f32_16x16x32_bf16 v[96:99], v[196:199], v[164:167], v[96:99]
	v_mfma_f32_16x16x32_bf16 v[84:87], v[188:191], v[172:175], v[84:87]
	v_mfma_f32_16x16x32_bf16 v[80:83], v[196:199], v[172:175], v[80:83]
	v_mfma_f32_16x16x32_bf16 v[68:71], v[188:191], v[180:183], v[68:71]
	v_mfma_f32_16x16x32_bf16 v[64:67], v[196:199], v[180:183], v[64:67]
	v_mfma_f32_16x16x32_bf16 v[116:119], v[192:195], v[160:163], v[116:119]
	v_mfma_f32_16x16x32_bf16 v[112:115], v[200:203], v[160:163], v[112:115]
	v_mfma_f32_16x16x32_bf16 v[100:103], v[192:195], v[168:171], v[100:103]
	v_mfma_f32_16x16x32_bf16 v[96:99], v[200:203], v[168:171], v[96:99]
	v_mfma_f32_16x16x32_bf16 v[84:87], v[192:195], v[176:179], v[84:87]
	v_mfma_f32_16x16x32_bf16 v[80:83], v[200:203], v[176:179], v[80:83]
	v_mfma_f32_16x16x32_bf16 v[68:71], v[192:195], v[184:187], v[68:71]
	s_setprio 0
	v_mfma_f32_16x16x32_bf16 v[64:67], v[200:203], v[184:187], v[64:67]
	s_barrier
	ds_read_b128 v[156:159], v135 offset:49152
	ds_read_b128 v[160:163], v135 offset:50176
	ds_read_b128 v[164:167], v135 offset:51200
	ds_read_b128 v[168:171], v135 offset:52224
	ds_read_b128 v[172:175], v135 offset:53248
	ds_read_b128 v[176:179], v135 offset:54272
	ds_read_b128 v[180:183], v135 offset:55296
	ds_read_b128 v[184:187], v135 offset:56320
	global_load_lds_dwordx4 v[204:205], off
	s_mov_b32 m0, s44
	v_lshl_add_u64 v[204:205], s[26:27], 0, v[130:131]
	global_load_lds_dwordx4 v[204:205], off
	s_barrier
; __device__ __forceinline__ unsigned cvt_pk_bf16(float lo, float hi) { unsigned r; asm volatile("v_cvt_pk_bf16_f32 %0, %1, %2" : "=v"(r) : "v"(lo), "v"(hi)); return r; }
; #define PG8_STAGE(bufoff, gbase, voff) do { _Pragma("unroll") for (int _i = 0; _i < 2; ++_i) \
;         __builtin_amdgcn_global_load_lds((const unsigned*)((const char*)(gbase) + (voff)[_i]), (LAS unsigned*)(lds + (bufoff) + ldsw + _i * 8192), 16, 0, 0); } while (0)
; #define PG8_MMA(ai, bj, At, Bt) do { __builtin_amdgcn_s_setprio(1); _Pragma("unroll") for (int m = 0; m < 4; ++m) _Pragma("unroll") for (int n = 0; n < 2; ++n) _Pragma("unroll") for (int k = 0; k < 2; ++k) \
;         acc[ai][bj][m][n] = __builtin_amdgcn_mfma_f32_16x16x32_bf16(Bt[n][k], At[m][k], acc[ai][bj][m][n], 0, 0, 0); __builtin_amdgcn_s_setprio(0); } while (0)
; #define PG8_WAIT_V(n) asm volatile("s_waitcnt vmcnt(" #n ")" ::: "memory")
; #define PG8_WAIT_L(n) asm volatile("s_waitcnt lgkmcnt(" #n ")" ::: "memory")
; #define PG8_BAR __builtin_amdgcn_s_barrier()
; #define PG8_SCHED __builtin_amdgcn_sched_barrier(0)
; template <class Epi>
; __device__ __forceinline__ void gemm_phase(LAS unsigned char* lds, const Gemm g, const StaticOrder& S, const Epi& E) {
;     ...
;             PG8_BAR; PG8_WAIT_L(0); PG8_MMA(1, 0, At, B0); PG8_BAR; PG8_SCHED;
;             PG8_STAGE(PG8_SB(1, 1), b3 + hstepB, voffB);
;             PG8_WAIT_V(6); PG8_BAR; PG8_MMA(1, 1, At, B1); PG8_BAR;
;     __device__ __forceinline__ void operator()(const f32x4 (&acc)[2][2][4][2], const Unit& u, int wr, int wc, int fr, int fq) const {
;         const int row0 = u.pm * BM + wr * 64 + fr, col0 = u.pn * BM + wc * 32 + 8 * fq;
; #pragma unroll
;         for (int ai = 0; ai < 2; ++ai)
; #pragma unroll
;             for (int m = 0; m < 4; ++m) {
;                 const int rowi = row0 + ai * HALF + m * 16;
; #pragma unroll
;                 for (int bj = 0; bj < 2; ++bj) {
;                     f32x4 v0 = acc[ai][bj][m][0], v1 = acc[ai][bj][m][1];
; #pragma unroll
;                     for (int j = 0; j < 4; ++j) { const float a = fmaxf(v0[j], 0.f), b = fmaxf(v1[j], 0.f); v0[j] = a * a; v1[j] = b * b; }
;                     u32x4 w; w.x = cvt_pk_bf16(v0[0], v0[1]); w.y = cvt_pk_bf16(v0[2], v0[3]); w.z = cvt_pk_bf16(v1[0], v1[1]); w.w = cvt_pk_bf16(v1[2], v1[3]);
;                     *(u32x4*)(O + tiled_off(rowi, col0 + bj * HALF, DFF / 64)) = w;
	s_waitcnt lgkmcnt(0)
	s_setprio 1
	v_mfma_f32_16x16x32_bf16 v[60:63], v[136:139], v[156:159], v[60:63]
	v_mfma_f32_16x16x32_bf16 v[56:59], v[144:147], v[156:159], v[56:59]
	v_mfma_f32_16x16x32_bf16 v[44:47], v[136:139], v[164:167], v[44:47]
	v_mfma_f32_16x16x32_bf16 v[40:43], v[144:147], v[164:167], v[40:43]
	v_mfma_f32_16x16x32_bf16 v[28:31], v[136:139], v[172:175], v[28:31]
	v_mfma_f32_16x16x32_bf16 v[24:27], v[144:147], v[172:175], v[24:27]
	v_mfma_f32_16x16x32_bf16 v[12:15], v[136:139], v[180:183], v[12:15]
	v_mfma_f32_16x16x32_bf16 v[8:11], v[144:147], v[180:183], v[8:11]
	v_mfma_f32_16x16x32_bf16 v[60:63], v[140:143], v[160:163], v[60:63]
	v_mfma_f32_16x16x32_bf16 v[56:59], v[148:151], v[160:163], v[56:59]
	v_mfma_f32_16x16x32_bf16 v[44:47], v[140:143], v[168:171], v[44:47]
	v_mfma_f32_16x16x32_bf16 v[40:43], v[148:151], v[168:171], v[40:43]
	v_mfma_f32_16x16x32_bf16 v[28:31], v[140:143], v[176:179], v[28:31]
	v_mfma_f32_16x16x32_bf16 v[24:27], v[148:151], v[176:179], v[24:27]
	v_mfma_f32_16x16x32_bf16 v[12:15], v[140:143], v[184:187], v[12:15]
	s_setprio 0
	v_mfma_f32_16x16x32_bf16 v[8:11], v[148:151], v[184:187], v[8:11]
	s_barrier
	s_add_u32 s24, s24, 0x84000
	s_addc_u32 s25, s25, 0
	s_add_i32 s26, s56, s36
	s_mov_b32 m0, s26
	v_lshl_add_u64 v[136:137], s[24:25], 0, v[128:129]
	global_load_lds_dwordx4 v[136:137], off
	s_add_i32 m0, s26, 0x2000
	v_lshl_add_u64 v[136:137], s[24:25], 0, v[130:131]
	global_load_lds_dwordx4 v[136:137], off
	s_waitcnt vmcnt(6)
	s_barrier
	s_setprio 1
	v_mfma_f32_16x16x32_bf16 v[52:55], v[188:191], v[156:159], v[52:55]
	v_mfma_f32_16x16x32_bf16 v[48:51], v[196:199], v[156:159], v[48:51]
	s_add_i32 s54, s54, 2
	s_add_u32 s22, s22, 0x8000
	s_addc_u32 s23, s23, 0
	s_add_u32 s51, s51, 0x8000
	s_addc_u32 s52, s52, 0
	v_mfma_f32_16x16x32_bf16 v[36:39], v[188:191], v[164:167], v[36:39]
	v_mfma_f32_16x16x32_bf16 v[32:35], v[196:199], v[164:167], v[32:35]
	v_mfma_f32_16x16x32_bf16 v[20:23], v[188:191], v[172:175], v[20:23]
	v_mfma_f32_16x16x32_bf16 v[16:19], v[196:199], v[172:175], v[16:19]
	v_mfma_f32_16x16x32_bf16 v[4:7], v[188:191], v[180:183], v[4:7]
	v_mfma_f32_16x16x32_bf16 v[0:3], v[196:199], v[180:183], v[0:3]
	v_mfma_f32_16x16x32_bf16 v[52:55], v[192:195], v[160:163], v[52:55]
	v_mfma_f32_16x16x32_bf16 v[48:51], v[200:203], v[160:163], v[48:51]
	v_mfma_f32_16x16x32_bf16 v[36:39], v[192:195], v[168:171], v[36:39]
	v_mfma_f32_16x16x32_bf16 v[32:35], v[200:203], v[168:171], v[32:35]
	v_mfma_f32_16x16x32_bf16 v[20:23], v[192:195], v[176:179], v[20:23]
	v_mfma_f32_16x16x32_bf16 v[16:19], v[200:203], v[176:179], v[16:19]
	v_mfma_f32_16x16x32_bf16 v[4:7], v[192:195], v[184:187], v[4:7]
	s_cmp_gt_u32 s54, 29
	s_setprio 0
	v_mfma_f32_16x16x32_bf16 v[0:3], v[200:203], v[184:187], v[0:3]
	s_barrier
	s_cbranch_scc0 .LBB0_141
	s_lshl_b32 s24, s20, 8
	s_lshl_b32 s5, s21, 8
	s_add_i32 s24, s24, s41
	s_or_b32 s5, s5, s42
	s_and_b32 s22, s24, 0xffffff80
	s_ashr_i32 s5, s5, 6
	s_add_i32 s20, s22, s5
	s_ashr_i32 s21, s20, 31
	v_max_f32_e32 v120, 0, v120
	s_lshl_b64 s[20:21], s[20:21], 14
	v_readlane_b32 s26, v252, 57
	v_or_b32_e32 v136, s24, v132
	v_mul_f32_e32 v140, v120, v120
	v_max_f32_e32 v121, 0, v121
	v_max_f32_e32 v122, 0, v122
	v_readlane_b32 s27, v252, 58
	s_add_u32 s20, s26, s20
	v_lshlrev_b32_e32 v137, 6, v136
	s_movk_i32 s28, 0x3c0
	v_lshlrev_b32_e32 v138, 2, v136
	v_max_f32_e32 v120, 0, v125
	v_mul_f32_e32 v125, v121, v121
	v_max_f32_e32 v121, v126, v126
	v_mul_f32_e32 v126, v122, v122
	s_addc_u32 s21, s27, s21
	s_or_b32 s15, s5, 2
	v_and_or_b32 v137, v137, s28, v133
	v_and_b32_e32 v138, 32, v138
	v_max_f32_e32 v124, 0, v124
	v_mul_f32_e32 v120, v120, v120
	v_max_f32_e32 v121, 0, v121
	v_max_f32_e32 v122, 0, v127
	v_max_f32_e32 v123, 0, v123
	s_add_i32 s22, s15, s22
	v_bitop3_b32 v139, v137, s46, v138 bitop3:0xde
	v_mul_f32_e32 v124, v124, v124
	v_mul_f32_e32 v121, v121, v121
	v_mul_f32_e32 v122, v122, v122
	v_mul_f32_e32 v123, v123, v123
	v_cvt_pk_bf16_f32 v120, v124, v120
	v_max_f32_e32 v112, 0, v112
	v_max_f32_e32 v113, 0, v113
	s_ashr_i32 s23, s22, 31
	v_cvt_pk_bf16_f32 v121, v121, v122
	v_cvt_pk_bf16_f32 v122, v140, v125
	v_cvt_pk_bf16_f32 v123, v126, v123
	global_store_dwordx4 v139, v[120:123], s[20:21]
	v_max_f32_e32 v114, 0, v114
	s_lshl_b64 s[22:23], s[22:23], 14
	v_mul_f32_e32 v120, v112, v112
	v_max_f32_e32 v112, v117, v117
	v_mul_f32_e32 v117, v113, v113
	v_max_f32_e32 v112, 0, v112
	v_max_f32_e32 v113, 0, v118
	v_mul_f32_e32 v118, v114, v114
	s_add_u32 s22, s26, s22
	v_max_f32_e32 v116, 0, v116
	v_mul_f32_e32 v112, v112, v112
	v_mul_f32_e32 v113, v113, v113
	v_max_f32_e32 v114, 0, v119
	v_max_f32_e32 v115, 0, v115
	s_addc_u32 s23, s27, s23
	s_or_b32 s25, s24, 16
	v_mul_f32_e32 v116, v116, v116
	v_mul_f32_e32 v114, v114, v114
	v_mul_f32_e32 v115, v115, v115
	v_cvt_pk_bf16_f32 v112, v116, v112
	v_cvt_pk_bf16_f32 v113, v113, v114
	s_lshr_b32 s25, s25, 3
	v_max_f32_e32 v104, 0, v104
	v_cvt_pk_bf16_f32 v114, v120, v117
	v_cvt_pk_bf16_f32 v115, v118, v115
	global_store_dwordx4 v139, v[112:115], s[22:23]
	s_and_b32 s25, s25, 10
	v_max_f32_e32 v105, 0, v105
	v_mul_f32_e32 v113, v104, v104
	v_max_f32_e32 v106, 0, v106
	s_or_b32 s25, s25, s45
	v_max_f32_e32 v104, 0, v109
	v_mul_f32_e32 v109, v105, v105
	v_max_f32_e32 v105, v110, v110
	v_mul_f32_e32 v110, v106, v106
	s_lshl_b32 s25, s25, 10
	v_max_f32_e32 v108, 0, v108
	v_mul_f32_e32 v104, v104, v104
	v_max_f32_e32 v105, 0, v105
	v_max_f32_e32 v106, 0, v111
	v_max_f32_e32 v107, 0, v107
	v_bitop3_b32 v112, v137, s25, v138 bitop3:0xde
	v_mul_f32_e32 v108, v108, v108
	v_mul_f32_e32 v105, v105, v105
	v_mul_f32_e32 v106, v106, v106
	v_mul_f32_e32 v107, v107, v107
; __device__ __forceinline__ unsigned cvt_pk_bf16(float lo, float hi) { unsigned r; asm volatile("v_cvt_pk_bf16_f32 %0, %1, %2" : "=v"(r) : "v"(lo), "v"(hi)); return r; }
;     __device__ __forceinline__ void operator()(const f32x4 (&acc)[2][2][4][2], const Unit& u, int wr, int wc, int fr, int fq) const {
;     ...
;         for (int ai = 0; ai < 2; ++ai)
; #pragma unroll
;             for (int m = 0; m < 4; ++m) {
;                 const int rowi = row0 + ai * HALF + m * 16;
; #pragma unroll
;                 for (int bj = 0; bj < 2; ++bj) {
;                     f32x4 v0 = acc[ai][bj][m][0], v1 = acc[ai][bj][m][1];
; #pragma unroll
;                     for (int j = 0; j < 4; ++j) { const float a = fmaxf(v0[j], 0.f), b = fmaxf(v1[j], 0.f); v0[j] = a * a; v1[j] = b * b; }
;                     u32x4 w; w.x = cvt_pk_bf16(v0[0], v0[1]); w.y = cvt_pk_bf16(v0[2], v0[3]); w.z = cvt_pk_bf16(v1[0], v1[1]); w.w = cvt_pk_bf16(v1[2], v1[3]);
;                     *(u32x4*)(O + tiled_off(rowi, col0 + bj * HALF, DFF / 64)) = w;
	v_cvt_pk_bf16_f32 v104, v108, v104
	v_max_f32_e32 v96, 0, v96
	v_max_f32_e32 v97, 0, v97
	v_cvt_pk_bf16_f32 v105, v105, v106
	v_cvt_pk_bf16_f32 v106, v113, v109
	v_cvt_pk_bf16_f32 v107, v110, v107
	global_store_dwordx4 v112, v[104:107], s[20:21]
	s_nop 0
	v_max_f32_e32 v98, 0, v98
	v_mul_f32_e32 v104, v96, v96
	v_max_f32_e32 v96, v101, v101
	v_mul_f32_e32 v101, v97, v97
	v_max_f32_e32 v96, 0, v96
	v_max_f32_e32 v97, 0, v102
	v_mul_f32_e32 v102, v98, v98
	v_max_f32_e32 v100, 0, v100
	v_mul_f32_e32 v96, v96, v96
	v_mul_f32_e32 v97, v97, v97
	v_max_f32_e32 v98, 0, v103
	v_max_f32_e32 v99, 0, v99
	s_or_b32 s25, s24, 32
	v_mul_f32_e32 v100, v100, v100
	v_mul_f32_e32 v98, v98, v98
	v_mul_f32_e32 v99, v99, v99
	v_cvt_pk_bf16_f32 v96, v100, v96
	v_cvt_pk_bf16_f32 v97, v97, v98
	s_lshr_b32 s25, s25, 3
	v_max_f32_e32 v88, 0, v88
	v_cvt_pk_bf16_f32 v98, v104, v101
	v_cvt_pk_bf16_f32 v99, v102, v99
	global_store_dwordx4 v112, v[96:99], s[22:23]
	s_and_b32 s25, s25, 12
	v_max_f32_e32 v89, 0, v89
	v_mul_f32_e32 v97, v88, v88
	v_max_f32_e32 v90, 0, v90
	s_or_b32 s25, s25, s45
	v_max_f32_e32 v88, 0, v93
	v_mul_f32_e32 v93, v89, v89
	v_max_f32_e32 v89, v94, v94
	v_mul_f32_e32 v94, v90, v90
	s_lshl_b32 s25, s25, 10
	v_max_f32_e32 v92, 0, v92
	v_mul_f32_e32 v88, v88, v88
	v_max_f32_e32 v89, 0, v89
	v_max_f32_e32 v90, 0, v95
	v_max_f32_e32 v91, 0, v91
	v_bitop3_b32 v96, v137, s25, v138 bitop3:0xde
	v_mul_f32_e32 v92, v92, v92
	v_mul_f32_e32 v89, v89, v89
	v_mul_f32_e32 v90, v90, v90
	v_mul_f32_e32 v91, v91, v91
	v_cvt_pk_bf16_f32 v88, v92, v88
	v_max_f32_e32 v80, 0, v80
	v_max_f32_e32 v81, 0, v81
	v_cvt_pk_bf16_f32 v89, v89, v90
	v_cvt_pk_bf16_f32 v90, v97, v93
	v_cvt_pk_bf16_f32 v91, v94, v91
	global_store_dwordx4 v96, v[88:91], s[20:21]
	s_nop 0
	v_max_f32_e32 v82, 0, v82
	v_mul_f32_e32 v88, v80, v80
	v_max_f32_e32 v80, v85, v85
	v_mul_f32_e32 v85, v81, v81
	v_max_f32_e32 v80, 0, v80
	v_max_f32_e32 v81, 0, v86
	v_mul_f32_e32 v86, v82, v82
	v_max_f32_e32 v84, 0, v84
	v_mul_f32_e32 v80, v80, v80
	v_mul_f32_e32 v81, v81, v81
	v_max_f32_e32 v82, 0, v87
	v_max_f32_e32 v83, 0, v83
	s_or_b32 s24, s24, 48
	v_mul_f32_e32 v84, v84, v84
	v_mul_f32_e32 v82, v82, v82
	v_mul_f32_e32 v83, v83, v83
	v_cvt_pk_bf16_f32 v80, v84, v80
	v_cvt_pk_bf16_f32 v81, v81, v82
	s_lshr_b32 s24, s24, 3
	v_max_f32_e32 v72, 0, v72
	v_cvt_pk_bf16_f32 v82, v88, v85
	v_cvt_pk_bf16_f32 v83, v86, v83
	global_store_dwordx4 v96, v[80:83], s[22:23]
	s_and_b32 s24, s24, 14
	v_max_f32_e32 v73, 0, v73
	v_mul_f32_e32 v81, v72, v72
	v_max_f32_e32 v74, 0, v74
	s_or_b32 s24, s24, s45
	v_max_f32_e32 v72, 0, v77
	v_mul_f32_e32 v77, v73, v73
	v_max_f32_e32 v73, v78, v78
	v_mul_f32_e32 v78, v74, v74
	s_lshl_b32 s24, s24, 10
	v_max_f32_e32 v76, 0, v76
	v_mul_f32_e32 v72, v72, v72
	v_max_f32_e32 v73, 0, v73
	v_max_f32_e32 v74, 0, v79
	v_max_f32_e32 v75, 0, v75
	v_bitop3_b32 v80, v137, s24, v138 bitop3:0xde
	v_mul_f32_e32 v76, v76, v76
	v_mul_f32_e32 v73, v73, v73
	v_mul_f32_e32 v74, v74, v74
	v_mul_f32_e32 v75, v75, v75
	v_cvt_pk_bf16_f32 v72, v76, v72
	v_max_f32_e32 v64, 0, v64
	v_cvt_pk_bf16_f32 v73, v73, v74
	v_cvt_pk_bf16_f32 v74, v81, v77
	v_cvt_pk_bf16_f32 v75, v78, v75
	global_store_dwordx4 v80, v[72:75], s[20:21]
	v_max_f32_e32 v65, 0, v65
	v_max_f32_e32 v66, 0, v66
	v_mul_f32_e32 v72, v64, v64
	v_max_f32_e32 v64, 0, v69
	v_mul_f32_e32 v69, v65, v65
	v_max_f32_e32 v65, v70, v70
	v_mul_f32_e32 v70, v66, v66
	v_max_f32_e32 v68, 0, v68
	v_mul_f32_e32 v64, v64, v64
	v_max_f32_e32 v65, 0, v65
	v_max_f32_e32 v66, 0, v71
	v_max_f32_e32 v67, 0, v67
	v_mul_f32_e32 v68, v68, v68
	v_mul_f32_e32 v65, v65, v65
	v_mul_f32_e32 v66, v66, v66
	v_mul_f32_e32 v67, v67, v67
	v_cvt_pk_bf16_f32 v64, v68, v64
	v_cvt_pk_bf16_f32 v65, v65, v66
	v_cvt_pk_bf16_f32 v66, v72, v69
	v_cvt_pk_bf16_f32 v67, v70, v67
	global_store_dwordx4 v80, v[64:67], s[22:23]
	s_nop 0
	v_max_f32_e32 v56, 0, v56
	v_add_u32_e32 v64, 0x80, v136
	v_and_b32_e32 v65, 0xffffff80, v64
	v_lshlrev_b32_e32 v66, 6, v64
	v_lshlrev_b32_e32 v64, 2, v64
	v_and_or_b32 v66, v66, s28, v133
	v_and_b32_e32 v64, 32, v64
	v_bitop3_b32 v152, v66, s46, v64 bitop3:0xde
	v_mul_f32_e32 v64, v56, v56
	v_max_f32_e32 v57, 0, v57
	v_max_f32_e32 v58, 0, v58
	v_max_f32_e32 v60, 0, v60
	v_max_f32_e32 v56, 0, v61
	v_mul_f32_e32 v61, v57, v57
	v_max_f32_e32 v57, v62, v62
	v_mul_f32_e32 v62, v58, v58
	v_mul_f32_e32 v60, v60, v60
	v_mul_f32_e32 v56, v56, v56
	v_max_f32_e32 v57, 0, v57
	v_max_f32_e32 v58, 0, v63
	v_mul_f32_e32 v57, v57, v57
	v_mul_f32_e32 v58, v58, v58
	v_cvt_pk_bf16_f32 v56, v60, v56
	v_add_u32_e32 v60, s5, v65
	v_cvt_pk_bf16_f32 v57, v57, v58
	v_cvt_pk_bf16_f32 v58, v64, v61
	v_ashrrev_i32_e32 v61, 31, v60
	v_max_f32_e32 v59, 0, v59
	v_lshlrev_b64 v[60:61], 14, v[60:61]
	v_mul_f32_e32 v59, v59, v59
	v_lshl_add_u64 v[60:61], s[26:27], 0, v[60:61]
	v_cvt_pk_bf16_f32 v59, v62, v59
	v_lshl_add_u64 v[62:63], v[60:61], 0, v[152:153]
	v_max_f32_e32 v48, 0, v48
	global_store_dwordx4 v[62:63], v[56:59], off
	s_nop 0
	v_max_f32_e32 v49, 0, v49
	v_mul_f32_e32 v56, v48, v48
	v_max_f32_e32 v50, 0, v50
	v_max_f32_e32 v52, 0, v52
	v_max_f32_e32 v48, 0, v53
	v_mul_f32_e32 v53, v49, v49
	v_max_f32_e32 v49, v54, v54
	v_mul_f32_e32 v54, v50, v50
	v_mul_f32_e32 v52, v52, v52
	v_mul_f32_e32 v48, v48, v48
	v_max_f32_e32 v49, 0, v49
	v_max_f32_e32 v50, 0, v55
	v_mul_f32_e32 v49, v49, v49
	v_mul_f32_e32 v50, v50, v50
	v_cvt_pk_bf16_f32 v48, v52, v48
	v_add_u32_e32 v52, s15, v65
	v_cvt_pk_bf16_f32 v49, v49, v50
	v_cvt_pk_bf16_f32 v50, v56, v53
	v_ashrrev_i32_e32 v53, 31, v52
	v_max_f32_e32 v51, 0, v51
	v_lshlrev_b64 v[52:53], 14, v[52:53]
	v_mul_f32_e32 v51, v51, v51
; __device__ __forceinline__ unsigned cvt_pk_bf16(float lo, float hi) { unsigned r; asm volatile("v_cvt_pk_bf16_f32 %0, %1, %2" : "=v"(r) : "v"(lo), "v"(hi)); return r; }
; #define PG8_WAIT_V(n) asm volatile("s_waitcnt vmcnt(" #n ")" ::: "memory")
; #define PG8_BAR __builtin_amdgcn_s_barrier()
; template <class Epi>
; __device__ __forceinline__ void gemm_phase(LAS unsigned char* lds, const Gemm g, const StaticOrder& S, const Epi& E) {
;     ...
;         if (!has_next) break;
; #pragma unroll
;         for (int a = 0; a < 2; ++a)
; #pragma unroll
;             for (int b = 0; b < 2; ++b)
; #pragma unroll
;                 for (int m = 0; m < 4; ++m)
; #pragma unroll
;                     for (int n = 0; n < 2; ++n) acc[a][b][m][n] = (f32x4){0.f, 0.f, 0.f, 0.f};
;         cur = nxt; cA = nA; cB = nB; ++ui;
;     }
;     PG8_WAIT_V(0);
;     if (wr == 0) PG8_BAR;
;     __device__ __forceinline__ void operator()(const f32x4 (&acc)[2][2][4][2], const Unit& u, int wr, int wc, int fr, int fq) const {
;     ...
;         for (int ai = 0; ai < 2; ++ai)
; #pragma unroll
;             for (int m = 0; m < 4; ++m) {
;                 const int rowi = row0 + ai * HALF + m * 16;
; #pragma unroll
;                 for (int bj = 0; bj < 2; ++bj) {
;                     f32x4 v0 = acc[ai][bj][m][0], v1 = acc[ai][bj][m][1];
; #pragma unroll
;                     for (int j = 0; j < 4; ++j) { const float a = fmaxf(v0[j], 0.f), b = fmaxf(v1[j], 0.f); v0[j] = a * a; v1[j] = b * b; }
;                     u32x4 w; w.x = cvt_pk_bf16(v0[0], v0[1]); w.y = cvt_pk_bf16(v0[2], v0[3]); w.z = cvt_pk_bf16(v1[0], v1[1]); w.w = cvt_pk_bf16(v1[2], v1[3]);
;                     *(u32x4*)(O + tiled_off(rowi, col0 + bj * HALF, DFF / 64)) = w;
	v_lshl_add_u64 v[52:53], s[26:27], 0, v[52:53]
	v_cvt_pk_bf16_f32 v51, v54, v51
	v_lshl_add_u64 v[54:55], v[52:53], 0, v[152:153]
	global_store_dwordx4 v[54:55], v[48:51], off
	s_nop 1
	v_add_u32_e32 v48, 0x90, v136
	v_lshrrev_b32_e32 v49, 3, v48
	v_and_or_b32 v49, v49, 10, s45
	v_lshlrev_b32_e32 v50, 6, v48
	v_lshlrev_b32_e32 v48, 2, v48
	v_and_or_b32 v50, v50, s28, v133
	v_lshlrev_b32_e32 v49, 10, v49
	v_and_b32_e32 v48, 32, v48
	v_max_f32_e32 v40, 0, v40
	v_max_f32_e32 v41, 0, v41
	v_max_f32_e32 v42, 0, v42
	v_bitop3_b32 v152, v50, v49, v48 bitop3:0xde
	v_mul_f32_e32 v48, v40, v40
	v_max_f32_e32 v40, v45, v45
	v_mul_f32_e32 v45, v41, v41
	v_max_f32_e32 v41, v46, v46
	v_mul_f32_e32 v46, v42, v42
	v_max_f32_e32 v44, 0, v44
	v_max_f32_e32 v40, 0, v40
	v_max_f32_e32 v41, 0, v41
	v_max_f32_e32 v42, 0, v47
	v_mul_f32_e32 v44, v44, v44
	v_mul_f32_e32 v40, v40, v40
	v_mul_f32_e32 v41, v41, v41
	v_max_f32_e32 v43, 0, v43
	v_mul_f32_e32 v42, v42, v42
	v_mul_f32_e32 v43, v43, v43
	v_cvt_pk_bf16_f32 v40, v44, v40
	v_cvt_pk_bf16_f32 v41, v41, v42
	v_cvt_pk_bf16_f32 v42, v48, v45
	v_lshl_add_u64 v[44:45], v[60:61], 0, v[152:153]
	v_max_f32_e32 v32, 0, v32
	v_max_f32_e32 v33, 0, v33
	v_max_f32_e32 v34, 0, v34
	v_cvt_pk_bf16_f32 v43, v46, v43
	global_store_dwordx4 v[44:45], v[40:43], off
	s_nop 0
	v_max_f32_e32 v36, 0, v36
	v_mul_f32_e32 v40, v32, v32
	v_max_f32_e32 v32, v37, v37
	v_mul_f32_e32 v37, v33, v33
	v_max_f32_e32 v33, v38, v38
	v_mul_f32_e32 v38, v34, v34
	v_max_f32_e32 v32, 0, v32
	v_max_f32_e32 v33, 0, v33
	v_max_f32_e32 v34, 0, v39
	v_mul_f32_e32 v36, v36, v36
	v_mul_f32_e32 v32, v32, v32
	v_mul_f32_e32 v33, v33, v33
	v_max_f32_e32 v35, 0, v35
	v_mul_f32_e32 v34, v34, v34
	v_mul_f32_e32 v35, v35, v35
	v_cvt_pk_bf16_f32 v32, v36, v32
	v_cvt_pk_bf16_f32 v33, v33, v34
	v_cvt_pk_bf16_f32 v34, v40, v37
	v_lshl_add_u64 v[36:37], v[52:53], 0, v[152:153]
	v_cvt_pk_bf16_f32 v35, v38, v35
	global_store_dwordx4 v[36:37], v[32:35], off
	s_nop 1
	v_add_u32_e32 v32, 0xa0, v136
	v_lshrrev_b32_e32 v33, 3, v32
	v_and_or_b32 v33, v33, 12, s45
	v_lshlrev_b32_e32 v34, 6, v32
	v_lshlrev_b32_e32 v32, 2, v32
	v_and_or_b32 v34, v34, s28, v133
	v_lshlrev_b32_e32 v33, 10, v33
	v_and_b32_e32 v32, 32, v32
	v_max_f32_e32 v24, 0, v24
	v_max_f32_e32 v25, 0, v25
	v_max_f32_e32 v26, 0, v26
	v_bitop3_b32 v152, v34, v33, v32 bitop3:0xde
	v_mul_f32_e32 v32, v24, v24
	v_max_f32_e32 v24, v29, v29
	v_mul_f32_e32 v29, v25, v25
	v_max_f32_e32 v25, v30, v30
	v_mul_f32_e32 v30, v26, v26
	v_max_f32_e32 v28, 0, v28
	v_max_f32_e32 v24, 0, v24
	v_max_f32_e32 v25, 0, v25
	v_max_f32_e32 v26, 0, v31
	v_mul_f32_e32 v28, v28, v28
	v_mul_f32_e32 v24, v24, v24
	v_mul_f32_e32 v25, v25, v25
	v_max_f32_e32 v27, 0, v27
	v_mul_f32_e32 v26, v26, v26
	v_mul_f32_e32 v27, v27, v27
	v_cvt_pk_bf16_f32 v24, v28, v24
	v_cvt_pk_bf16_f32 v25, v25, v26
	v_cvt_pk_bf16_f32 v26, v32, v29
	v_lshl_add_u64 v[28:29], v[60:61], 0, v[152:153]
	v_max_f32_e32 v16, 0, v16
	v_max_f32_e32 v17, 0, v17
	v_max_f32_e32 v18, 0, v18
	v_cvt_pk_bf16_f32 v27, v30, v27
	global_store_dwordx4 v[28:29], v[24:27], off
	s_nop 0
	v_max_f32_e32 v20, 0, v20
	v_mul_f32_e32 v24, v16, v16
	v_max_f32_e32 v16, v21, v21
	v_mul_f32_e32 v21, v17, v17
	v_max_f32_e32 v17, v22, v22
	v_mul_f32_e32 v22, v18, v18
	v_max_f32_e32 v16, 0, v16
	v_max_f32_e32 v17, 0, v17
	v_max_f32_e32 v18, 0, v23
	v_mul_f32_e32 v20, v20, v20
	v_mul_f32_e32 v16, v16, v16
	v_mul_f32_e32 v17, v17, v17
	v_max_f32_e32 v19, 0, v19
	v_mul_f32_e32 v18, v18, v18
	v_mul_f32_e32 v19, v19, v19
	v_cvt_pk_bf16_f32 v16, v20, v16
	v_cvt_pk_bf16_f32 v17, v17, v18
	v_cvt_pk_bf16_f32 v18, v24, v21
	v_lshl_add_u64 v[20:21], v[52:53], 0, v[152:153]
	v_cvt_pk_bf16_f32 v19, v22, v19
	global_store_dwordx4 v[20:21], v[16:19], off
	s_nop 1
	v_add_u32_e32 v16, 0xb0, v136
	v_lshrrev_b32_e32 v17, 3, v16
	v_and_or_b32 v17, v17, 14, s45
	v_lshlrev_b32_e32 v18, 6, v16
	v_lshlrev_b32_e32 v16, 2, v16
	v_and_or_b32 v18, v18, s28, v133
	v_lshlrev_b32_e32 v17, 10, v17
	v_and_b32_e32 v16, 32, v16
	v_max_f32_e32 v8, 0, v8
	v_max_f32_e32 v9, 0, v9
	v_max_f32_e32 v10, 0, v10
	v_bitop3_b32 v152, v18, v17, v16 bitop3:0xde
	v_mul_f32_e32 v16, v8, v8
	v_max_f32_e32 v8, v13, v13
	v_mul_f32_e32 v13, v9, v9
	v_max_f32_e32 v9, v14, v14
	v_mul_f32_e32 v14, v10, v10
	v_max_f32_e32 v12, 0, v12
	v_max_f32_e32 v8, 0, v8
	v_max_f32_e32 v9, 0, v9
	v_max_f32_e32 v10, 0, v15
	v_mul_f32_e32 v12, v12, v12
	v_mul_f32_e32 v8, v8, v8
	v_mul_f32_e32 v9, v9, v9
	v_max_f32_e32 v11, 0, v11
	v_mul_f32_e32 v10, v10, v10
	v_mul_f32_e32 v11, v11, v11
	v_cvt_pk_bf16_f32 v8, v12, v8
	v_cvt_pk_bf16_f32 v9, v9, v10
	v_cvt_pk_bf16_f32 v10, v16, v13
	v_lshl_add_u64 v[12:13], v[60:61], 0, v[152:153]
	v_max_f32_e32 v0, 0, v0
	v_max_f32_e32 v1, 0, v1
	v_max_f32_e32 v2, 0, v2
	v_cvt_pk_bf16_f32 v11, v14, v11
	global_store_dwordx4 v[12:13], v[8:11], off
	s_nop 0
	v_max_f32_e32 v4, 0, v4
	v_mul_f32_e32 v8, v0, v0
	v_max_f32_e32 v0, v5, v5
	v_mul_f32_e32 v5, v1, v1
	v_max_f32_e32 v1, v6, v6
	v_mul_f32_e32 v6, v2, v2
	v_max_f32_e32 v0, 0, v0
	v_max_f32_e32 v1, 0, v1
	v_max_f32_e32 v2, 0, v7
	v_mul_f32_e32 v4, v4, v4
	v_mul_f32_e32 v0, v0, v0
	v_mul_f32_e32 v1, v1, v1
	v_max_f32_e32 v3, 0, v3
	v_mul_f32_e32 v2, v2, v2
	s_mov_b32 s54, 0xd00ab22c
	v_mul_f32_e32 v3, v3, v3
	v_cvt_pk_bf16_f32 v0, v4, v0
	v_cvt_pk_bf16_f32 v1, v1, v2
	v_cvt_pk_bf16_f32 v2, v8, v5
	v_lshl_add_u64 v[4:5], v[52:53], 0, v[152:153]
	s_and_b64 vcc, exec, s[0:1]
	s_mov_b32 s21, s4
	s_mov_b32 s20, s14
	s_mov_b64 s[24:25], s[18:19]
	s_mov_b64 s[22:23], s[16:17]
	s_mov_b32 s55, 0x3febb5fa
	v_cvt_pk_bf16_f32 v3, v6, v3
	global_store_dwordx4 v[4:5], v[0:3], off
	s_cbranch_vccz .LBB0_134
	s_waitcnt vmcnt(0)
	s_cmpk_gt_u32 s31, 0xff
	s_cbranch_scc1 .LBB0_145
	s_barrier

; #define PG8_STAGE(bufoff, gbase, voff) do { _Pragma("unroll") for (int _i = 0; _i < 2; ++_i) \
;         __builtin_amdgcn_global_load_lds((const unsigned*)((const char*)(gbase) + (voff)[_i]), (LAS unsigned*)(lds + (bufoff) + ldsw + _i * 8192), 16, 0, 0); } while (0)
; #define PG8_LDA(dst, b, h) do { _Pragma("unroll") for (int m = 0; m < 4; ++m) _Pragma("unroll") for (int k = 0; k < 2; ++k) dst[m][k] = *(const LAS bf16x8*)(lds + PG8_SA(b, h) + aoff + m * 2048 + k * 1024); } while (0)
; #define PG8_LDB(dst, b, h) do { _Pragma("unroll") for (int n = 0; n < 2; ++n) _Pragma("unroll") for (int k = 0; k < 2; ++k) dst[n][k] = *(const LAS bf16x8*)(lds + PG8_SB(b, h) + boff + n * 2048 + k * 1024); } while (0)
; #define PG8_MMA(ai, bj, At, Bt) do { __builtin_amdgcn_s_setprio(1); _Pragma("unroll") for (int m = 0; m < 4; ++m) _Pragma("unroll") for (int n = 0; n < 2; ++n) _Pragma("unroll") for (int k = 0; k < 2; ++k) \
;         acc[ai][bj][m][n] = __builtin_amdgcn_mfma_f32_16x16x32_bf16(Bt[n][k], At[m][k], acc[ai][bj][m][n], 0, 0, 0); __builtin_amdgcn_s_setprio(0); } while (0)
; #define PG8_WAIT_L(n) asm volatile("s_waitcnt lgkmcnt(" #n ")" ::: "memory")
; #define PG8_BAR __builtin_amdgcn_s_barrier()
; #define PG8_SCHED __builtin_amdgcn_sched_barrier(0)
; template <class Epi>
; __device__ __forceinline__ void gemm_phase(LAS unsigned char* lds, const Gemm g, const StaticOrder& S, const Epi& E) {
;     ...
;             const bool last = (t == nt - 2);
;             const char* a1 = cA + (size_t)(t + 1) * kstep;
;             const char* a2 = last ? nA : cA + (size_t)(t + 2) * kstep; const char* b2 = last ? nB : cB + (size_t)(t + 2) * kstep;
;             const char* a3 = a2 + kstep; const char* b3 = b2 + kstep;
;             PG8_LDB(B0, 0, 0); PG8_SCHED; PG8_LDA(At, 0, 0); PG8_STAGE(PG8_SA(1, 1), a1 + hstepA, voffA);
;             PG8_WAIT_L(8); PG8_BAR; PG8_WAIT_L(0); PG8_MMA(0, 0, At, B0); PG8_BAR; PG8_SCHED;
;             PG8_LDB(B1, 0, 1); PG8_STAGE(PG8_SB(0, 0), b2, voffB);
;             PG8_BAR; PG8_WAIT_L(0); PG8_MMA(0, 1, At, B1); PG8_BAR;
;             PG8_LDA(At, 0, 1); PG8_STAGE(PG8_SA(0, 0), a2, voffA);
;             PG8_BAR; PG8_WAIT_L(0); PG8_MMA(1, 0, At, B0); PG8_BAR; PG8_SCHED;
.LBB0_187:
	s_mov_b32 s55, 0x10000
	v_add_u32_e32 v140, s55, v207
	ds_read_b128 v[128:131], v140
	ds_read_b128 v[132:135], v140 offset:1024
	ds_read_b128 v[136:139], v140 offset:2048
	ds_read_b128 v[140:143], v140 offset:3072
	ds_read_b128 v[144:147], v209
	ds_read_b128 v[148:151], v209 offset:1024
	ds_read_b128 v[162:165], v209 offset:2048
	ds_read_b128 v[166:169], v209 offset:3072
	ds_read_b128 v[170:173], v209 offset:4096
	ds_read_b128 v[174:177], v209 offset:5120
	ds_read_b128 v[178:181], v209 offset:6144
	ds_read_b128 v[182:185], v209 offset:7168
	s_add_i32 s54, s22, 2
	s_add_u32 s23, s4, 0x4000
	s_addc_u32 s24, s5, 0
	s_cmp_eq_u32 s40, s22
	s_cselect_b32 s26, s6, s23
	s_cselect_b32 s27, s7, s24
	s_cselect_b32 s24, s20, s50
	s_cselect_b32 s25, s21, s51
	s_add_u32 s22, s26, 0x4000
	s_addc_u32 s23, s27, 0
	s_add_i32 m0, s33, 0xc000
	v_lshl_add_u64 v[186:187], s[4:5], 0, v[158:159]
	global_load_lds_dwordx4 v[186:187], off
	s_add_i32 m0, s33, 0xe000
	v_lshl_add_u64 v[186:187], s[4:5], 0, v[160:161]
	global_load_lds_dwordx4 v[186:187], off
	s_waitcnt lgkmcnt(8)
	s_barrier
	s_waitcnt lgkmcnt(0)
	s_setprio 1
	v_mfma_f32_16x16x32_bf16 v[124:127], v[128:131], v[144:147], v[124:127]
	v_mfma_f32_16x16x32_bf16 v[120:123], v[136:139], v[144:147], v[120:123]
	v_mfma_f32_16x16x32_bf16 v[116:119], v[128:131], v[162:165], v[116:119]
	v_mfma_f32_16x16x32_bf16 v[112:115], v[136:139], v[162:165], v[112:115]
	v_mfma_f32_16x16x32_bf16 v[108:111], v[128:131], v[170:173], v[108:111]
	v_mfma_f32_16x16x32_bf16 v[104:107], v[136:139], v[170:173], v[104:107]
	v_mfma_f32_16x16x32_bf16 v[100:103], v[128:131], v[178:181], v[100:103]
	v_mfma_f32_16x16x32_bf16 v[96:99], v[136:139], v[178:181], v[96:99]
	v_mfma_f32_16x16x32_bf16 v[124:127], v[132:135], v[148:151], v[124:127]
	v_mfma_f32_16x16x32_bf16 v[120:123], v[140:143], v[148:151], v[120:123]
	v_mfma_f32_16x16x32_bf16 v[116:119], v[132:135], v[166:169], v[116:119]
	v_mfma_f32_16x16x32_bf16 v[112:115], v[140:143], v[166:169], v[112:115]
	v_mfma_f32_16x16x32_bf16 v[108:111], v[132:135], v[174:177], v[108:111]
	v_mfma_f32_16x16x32_bf16 v[104:107], v[140:143], v[174:177], v[104:107]
	v_mfma_f32_16x16x32_bf16 v[100:103], v[132:135], v[182:185], v[100:103]
	s_setprio 0
	v_mfma_f32_16x16x32_bf16 v[96:99], v[140:143], v[182:185], v[96:99]
	s_barrier
	s_mov_b32 s58, 0x14000
	v_add_u32_e32 v198, s58, v207
	ds_read_b128 v[186:189], v198
	ds_read_b128 v[190:193], v198 offset:1024
	ds_read_b128 v[194:197], v198 offset:2048
	ds_read_b128 v[198:201], v198 offset:3072
	s_add_i32 s55, s55, s31
	s_mov_b32 m0, s55
	v_lshl_add_u64 v[202:203], s[24:25], 0, v[152:153]
	global_load_lds_dwordx4 v[202:203], off
	s_add_i32 m0, s55, 0x2000
	v_lshl_add_u64 v[202:203], s[24:25], 0, v[156:157]
	global_load_lds_dwordx4 v[202:203], off
	s_barrier
	s_waitcnt lgkmcnt(0)
	s_setprio 1
	v_mfma_f32_16x16x32_bf16 v[92:95], v[186:189], v[144:147], v[92:95]
	v_mfma_f32_16x16x32_bf16 v[88:91], v[194:197], v[144:147], v[88:91]
	s_mov_b32 m0, s33
	v_lshl_add_u64 v[202:203], s[26:27], 0, v[152:153]
	v_mfma_f32_16x16x32_bf16 v[84:87], v[186:189], v[162:165], v[84:87]
	v_mfma_f32_16x16x32_bf16 v[80:83], v[194:197], v[162:165], v[80:83]
	v_mfma_f32_16x16x32_bf16 v[76:79], v[186:189], v[170:173], v[76:79]
	v_mfma_f32_16x16x32_bf16 v[72:75], v[194:197], v[170:173], v[72:75]
	v_mfma_f32_16x16x32_bf16 v[68:71], v[186:189], v[178:181], v[68:71]
	v_mfma_f32_16x16x32_bf16 v[64:67], v[194:197], v[178:181], v[64:67]
	v_mfma_f32_16x16x32_bf16 v[92:95], v[190:193], v[148:151], v[92:95]
	v_mfma_f32_16x16x32_bf16 v[88:91], v[198:201], v[148:151], v[88:91]
	v_mfma_f32_16x16x32_bf16 v[84:87], v[190:193], v[166:169], v[84:87]
	v_mfma_f32_16x16x32_bf16 v[80:83], v[198:201], v[166:169], v[80:83]
	v_mfma_f32_16x16x32_bf16 v[76:79], v[190:193], v[174:177], v[76:79]
	v_mfma_f32_16x16x32_bf16 v[72:75], v[198:201], v[174:177], v[72:75]
	v_mfma_f32_16x16x32_bf16 v[68:71], v[190:193], v[182:185], v[68:71]
	s_setprio 0
	v_mfma_f32_16x16x32_bf16 v[64:67], v[198:201], v[182:185], v[64:67]
	s_barrier
	ds_read_b128 v[144:147], v209 offset:16384
	ds_read_b128 v[148:151], v209 offset:17408
	ds_read_b128 v[162:165], v209 offset:18432
	ds_read_b128 v[166:169], v209 offset:19456
	ds_read_b128 v[170:173], v209 offset:20480
	ds_read_b128 v[174:177], v209 offset:21504
	ds_read_b128 v[178:181], v209 offset:22528
	ds_read_b128 v[182:185], v209 offset:23552
	global_load_lds_dwordx4 v[202:203], off
	s_mov_b32 m0, s34
	v_lshl_add_u64 v[202:203], s[26:27], 0, v[156:157]
	global_load_lds_dwordx4 v[202:203], off
	s_barrier
	s_waitcnt lgkmcnt(0)
	s_setprio 1
	v_mfma_f32_16x16x32_bf16 v[60:63], v[128:131], v[144:147], v[60:63]
	v_mfma_f32_16x16x32_bf16 v[56:59], v[136:139], v[144:147], v[56:59]
	v_mfma_f32_16x16x32_bf16 v[52:55], v[128:131], v[162:165], v[52:55]
	v_mfma_f32_16x16x32_bf16 v[48:51], v[136:139], v[162:165], v[48:51]
	v_mfma_f32_16x16x32_bf16 v[44:47], v[128:131], v[170:173], v[44:47]
	v_mfma_f32_16x16x32_bf16 v[40:43], v[136:139], v[170:173], v[40:43]
	v_mfma_f32_16x16x32_bf16 v[36:39], v[128:131], v[178:181], v[36:39]
	v_mfma_f32_16x16x32_bf16 v[32:35], v[136:139], v[178:181], v[32:35]
	v_mfma_f32_16x16x32_bf16 v[60:63], v[132:135], v[148:151], v[60:63]
	v_mfma_f32_16x16x32_bf16 v[56:59], v[140:143], v[148:151], v[56:59]
	v_mfma_f32_16x16x32_bf16 v[52:55], v[132:135], v[166:169], v[52:55]
	v_mfma_f32_16x16x32_bf16 v[48:51], v[140:143], v[166:169], v[48:51]
	v_mfma_f32_16x16x32_bf16 v[44:47], v[132:135], v[174:177], v[44:47]
	v_mfma_f32_16x16x32_bf16 v[40:43], v[140:143], v[174:177], v[40:43]
	v_mfma_f32_16x16x32_bf16 v[36:39], v[132:135], v[182:185], v[36:39]
	s_setprio 0
	v_mfma_f32_16x16x32_bf16 v[32:35], v[140:143], v[182:185], v[32:35]
	s_barrier
; #define PG8_STAGE(bufoff, gbase, voff) do { _Pragma("unroll") for (int _i = 0; _i < 2; ++_i) \
;         __builtin_amdgcn_global_load_lds((const unsigned*)((const char*)(gbase) + (voff)[_i]), (LAS unsigned*)(lds + (bufoff) + ldsw + _i * 8192), 16, 0, 0); } while (0)
; #define PG8_LDA(dst, b, h) do { _Pragma("unroll") for (int m = 0; m < 4; ++m) _Pragma("unroll") for (int k = 0; k < 2; ++k) dst[m][k] = *(const LAS bf16x8*)(lds + PG8_SA(b, h) + aoff + m * 2048 + k * 1024); } while (0)
; #define PG8_LDB(dst, b, h) do { _Pragma("unroll") for (int n = 0; n < 2; ++n) _Pragma("unroll") for (int k = 0; k < 2; ++k) dst[n][k] = *(const LAS bf16x8*)(lds + PG8_SB(b, h) + boff + n * 2048 + k * 1024); } while (0)
; #define PG8_MMA(ai, bj, At, Bt) do { __builtin_amdgcn_s_setprio(1); _Pragma("unroll") for (int m = 0; m < 4; ++m) _Pragma("unroll") for (int n = 0; n < 2; ++n) _Pragma("unroll") for (int k = 0; k < 2; ++k) \
;         acc[ai][bj][m][n] = __builtin_amdgcn_mfma_f32_16x16x32_bf16(Bt[n][k], At[m][k], acc[ai][bj][m][n], 0, 0, 0); __builtin_amdgcn_s_setprio(0); } while (0)
; #define PG8_WAIT_V(n) asm volatile("s_waitcnt vmcnt(" #n ")" ::: "memory")
; #define PG8_WAIT_L(n) asm volatile("s_waitcnt lgkmcnt(" #n ")" ::: "memory")
; #define PG8_BAR __builtin_amdgcn_s_barrier()
; #define PG8_SCHED __builtin_amdgcn_sched_barrier(0)
; template <class Epi>
; __device__ __forceinline__ void gemm_phase(LAS unsigned char* lds, const Gemm g, const StaticOrder& S, const Epi& E) {
;     ...
;             PG8_STAGE(PG8_SB(0, 1), b2 + hstepB, voffB);
;             PG8_WAIT_V(6); PG8_BAR; PG8_MMA(1, 1, At, B1); PG8_BAR;
;             PG8_LDB(B0, 1, 0); PG8_SCHED; PG8_LDA(At, 1, 0); PG8_STAGE(PG8_SA(0, 1), a2 + hstepA, voffA);
;             PG8_WAIT_L(8); PG8_BAR; PG8_WAIT_L(0); PG8_MMA(0, 0, At, B0); PG8_BAR; PG8_SCHED;
;             PG8_LDB(B1, 1, 1); PG8_STAGE(PG8_SB(1, 0), b3, voffB);
;             PG8_BAR; PG8_WAIT_L(0); PG8_MMA(0, 1, At, B1); PG8_BAR;
;             PG8_LDA(At, 1, 1); PG8_STAGE(PG8_SA(1, 0), a3, voffA);
;             PG8_BAR; PG8_WAIT_L(0); PG8_MMA(1, 0, At, B0); PG8_BAR; PG8_SCHED;
	s_add_u32 s56, s24, s52
	s_addc_u32 s57, s25, 0
	s_add_i32 s55, s58, s31
	s_mov_b32 m0, s55
	v_lshl_add_u64 v[128:129], s[56:57], 0, v[152:153]
	global_load_lds_dwordx4 v[128:129], off
	s_add_i32 m0, s55, 0x2000
	v_lshl_add_u64 v[128:129], s[56:57], 0, v[156:157]
	global_load_lds_dwordx4 v[128:129], off
	s_waitcnt vmcnt(6)
	s_barrier
	s_setprio 1
	v_mfma_f32_16x16x32_bf16 v[28:31], v[186:189], v[144:147], v[28:31]
	v_mfma_f32_16x16x32_bf16 v[24:27], v[194:197], v[144:147], v[24:27]
	s_add_i32 s55, 0, 0x18000
	v_add_u32_e32 v140, s55, v207
	v_mfma_f32_16x16x32_bf16 v[20:23], v[186:189], v[162:165], v[20:23]
	v_mfma_f32_16x16x32_bf16 v[16:19], v[194:197], v[162:165], v[16:19]
	v_mfma_f32_16x16x32_bf16 v[12:15], v[186:189], v[170:173], v[12:15]
	v_mfma_f32_16x16x32_bf16 v[8:11], v[194:197], v[170:173], v[8:11]
	v_mfma_f32_16x16x32_bf16 v[4:7], v[186:189], v[178:181], v[4:7]
	v_mfma_f32_16x16x32_bf16 v[0:3], v[194:197], v[178:181], v[0:3]
	v_mfma_f32_16x16x32_bf16 v[28:31], v[190:193], v[148:151], v[28:31]
	v_mfma_f32_16x16x32_bf16 v[24:27], v[198:201], v[148:151], v[24:27]
	v_mfma_f32_16x16x32_bf16 v[20:23], v[190:193], v[166:169], v[20:23]
	v_mfma_f32_16x16x32_bf16 v[16:19], v[198:201], v[166:169], v[16:19]
	v_mfma_f32_16x16x32_bf16 v[12:15], v[190:193], v[174:177], v[12:15]
	v_mfma_f32_16x16x32_bf16 v[8:11], v[198:201], v[174:177], v[8:11]
	v_mfma_f32_16x16x32_bf16 v[4:7], v[190:193], v[182:185], v[4:7]
	s_setprio 0
	v_mfma_f32_16x16x32_bf16 v[0:3], v[198:201], v[182:185], v[0:3]
	s_barrier
	ds_read_b128 v[128:131], v140
	ds_read_b128 v[132:135], v140 offset:1024
	ds_read_b128 v[136:139], v140 offset:2048
	ds_read_b128 v[140:143], v140 offset:3072
	ds_read_b128 v[144:147], v209 offset:32768
	ds_read_b128 v[148:151], v209 offset:33792
	ds_read_b128 v[162:165], v209 offset:34816
	ds_read_b128 v[166:169], v209 offset:35840
	ds_read_b128 v[170:173], v209 offset:36864
	ds_read_b128 v[174:177], v209 offset:37888
	ds_read_b128 v[178:181], v209 offset:38912
	ds_read_b128 v[182:185], v209 offset:39936
	s_add_u32 s26, s26, s52
	s_addc_u32 s27, s27, 0
	s_mov_b32 m0, s35
	v_lshl_add_u64 v[186:187], s[26:27], 0, v[152:153]
	global_load_lds_dwordx4 v[186:187], off
	s_mov_b32 m0, s36
	v_lshl_add_u64 v[186:187], s[26:27], 0, v[156:157]
	global_load_lds_dwordx4 v[186:187], off
	s_waitcnt lgkmcnt(8)
	s_barrier
	s_waitcnt lgkmcnt(0)
	s_setprio 1
	v_mfma_f32_16x16x32_bf16 v[124:127], v[128:131], v[144:147], v[124:127]
	v_mfma_f32_16x16x32_bf16 v[120:123], v[136:139], v[144:147], v[120:123]
	v_mfma_f32_16x16x32_bf16 v[116:119], v[128:131], v[162:165], v[116:119]
	v_mfma_f32_16x16x32_bf16 v[112:115], v[136:139], v[162:165], v[112:115]
	v_mfma_f32_16x16x32_bf16 v[108:111], v[128:131], v[170:173], v[108:111]
	v_mfma_f32_16x16x32_bf16 v[104:107], v[136:139], v[170:173], v[104:107]
	v_mfma_f32_16x16x32_bf16 v[100:103], v[128:131], v[178:181], v[100:103]
	v_mfma_f32_16x16x32_bf16 v[96:99], v[136:139], v[178:181], v[96:99]
	v_mfma_f32_16x16x32_bf16 v[124:127], v[132:135], v[148:151], v[124:127]
	v_mfma_f32_16x16x32_bf16 v[120:123], v[140:143], v[148:151], v[120:123]
	v_mfma_f32_16x16x32_bf16 v[116:119], v[132:135], v[166:169], v[116:119]
	v_mfma_f32_16x16x32_bf16 v[112:115], v[140:143], v[166:169], v[112:115]
	v_mfma_f32_16x16x32_bf16 v[108:111], v[132:135], v[174:177], v[108:111]
	v_mfma_f32_16x16x32_bf16 v[104:107], v[140:143], v[174:177], v[104:107]
	v_mfma_f32_16x16x32_bf16 v[100:103], v[132:135], v[182:185], v[100:103]
	s_setprio 0
	v_mfma_f32_16x16x32_bf16 v[96:99], v[140:143], v[182:185], v[96:99]
	s_barrier
	s_mov_b32 s26, 0x1c000
	v_add_u32_e32 v198, s26, v207
	ds_read_b128 v[186:189], v198
	ds_read_b128 v[190:193], v198 offset:1024
	ds_read_b128 v[194:197], v198 offset:2048
	ds_read_b128 v[198:201], v198 offset:3072
	s_add_u32 s24, s24, 0x4000
	s_addc_u32 s25, s25, 0
	s_add_i32 s27, s55, s31
	s_mov_b32 m0, s27
	v_lshl_add_u64 v[202:203], s[24:25], 0, v[152:153]
	global_load_lds_dwordx4 v[202:203], off
	s_add_i32 m0, s27, 0x2000
	v_lshl_add_u64 v[202:203], s[24:25], 0, v[156:157]
	global_load_lds_dwordx4 v[202:203], off
	s_barrier
; #define PG8_STAGE(bufoff, gbase, voff) do { _Pragma("unroll") for (int _i = 0; _i < 2; ++_i) \
;         __builtin_amdgcn_global_load_lds((const unsigned*)((const char*)(gbase) + (voff)[_i]), (LAS unsigned*)(lds + (bufoff) + ldsw + _i * 8192), 16, 0, 0); } while (0)
; #define PG8_LDA(dst, b, h) do { _Pragma("unroll") for (int m = 0; m < 4; ++m) _Pragma("unroll") for (int k = 0; k < 2; ++k) dst[m][k] = *(const LAS bf16x8*)(lds + PG8_SA(b, h) + aoff + m * 2048 + k * 1024); } while (0)
; #define PG8_MMA(ai, bj, At, Bt) do { __builtin_amdgcn_s_setprio(1); _Pragma("unroll") for (int m = 0; m < 4; ++m) _Pragma("unroll") for (int n = 0; n < 2; ++n) _Pragma("unroll") for (int k = 0; k < 2; ++k) \
;         acc[ai][bj][m][n] = __builtin_amdgcn_mfma_f32_16x16x32_bf16(Bt[n][k], At[m][k], acc[ai][bj][m][n], 0, 0, 0); __builtin_amdgcn_s_setprio(0); } while (0)
; #define PG8_WAIT_V(n) asm volatile("s_waitcnt vmcnt(" #n ")" ::: "memory")
; #define PG8_WAIT_L(n) asm volatile("s_waitcnt lgkmcnt(" #n ")" ::: "memory")
; #define PG8_BAR __builtin_amdgcn_s_barrier()
; #define PG8_SCHED __builtin_amdgcn_sched_barrier(0)
; template <class Epi>
; __device__ __forceinline__ void gemm_phase(LAS unsigned char* lds, const Gemm g, const StaticOrder& S, const Epi& E) {
;     ...
;             PG8_BAR; PG8_WAIT_L(0); PG8_MMA(0, 1, At, B1); PG8_BAR;
;             PG8_LDA(At, 1, 1); PG8_STAGE(PG8_SA(1, 0), a3, voffA);
;             PG8_BAR; PG8_WAIT_L(0); PG8_MMA(1, 0, At, B0); PG8_BAR; PG8_SCHED;
;             PG8_STAGE(PG8_SB(1, 1), b3 + hstepB, voffB);
;             PG8_WAIT_V(6); PG8_BAR; PG8_MMA(1, 1, At, B1); PG8_BAR;
;     __device__ __forceinline__ void operator()(const f32x4 (&acc)[2][2][4][2], const Unit& u, int wr, int wc, int fr, int fq) const {
;         const int row0 = u.pm * BM + wr * 64 + fr, col0 = u.pn * BM + wc * 32 + 8 * fq;
;         const float* gb = gate + (size_t)(row0 >> 12) * (6 * DM);
;         const bool ln = stats != nullptr;
;         constexpr int GB[4] = {0, 4, 8, 16};
;         f32x2 st[4];
; #pragma unroll
;         for (int grp = 0; grp < 3; ++grp) {
;             u32x4 xv[8]; f32x4 cg[2][2], cl[2][2], cb[2][2];
;             if (grp == 0 || grp == 2) {
; #pragma unroll
;                 for (int m = 0; m < 4; ++m) st[m] = ln ? *(const f32x2*)(stats + 2 * (row0 + (grp ? HALF : 0) + m * 16)) : (f32x2){0.f, 1.f};
	s_waitcnt lgkmcnt(0)
	s_setprio 1
	v_mfma_f32_16x16x32_bf16 v[92:95], v[186:189], v[144:147], v[92:95]
	v_mfma_f32_16x16x32_bf16 v[88:91], v[194:197], v[144:147], v[88:91]
	s_mov_b32 m0, s38
	v_lshl_add_u64 v[202:203], s[22:23], 0, v[152:153]
	v_mfma_f32_16x16x32_bf16 v[84:87], v[186:189], v[162:165], v[84:87]
	v_mfma_f32_16x16x32_bf16 v[80:83], v[194:197], v[162:165], v[80:83]
	v_mfma_f32_16x16x32_bf16 v[76:79], v[186:189], v[170:173], v[76:79]
	v_mfma_f32_16x16x32_bf16 v[72:75], v[194:197], v[170:173], v[72:75]
	v_mfma_f32_16x16x32_bf16 v[68:71], v[186:189], v[178:181], v[68:71]
	v_mfma_f32_16x16x32_bf16 v[64:67], v[194:197], v[178:181], v[64:67]
	v_mfma_f32_16x16x32_bf16 v[92:95], v[190:193], v[148:151], v[92:95]
	v_mfma_f32_16x16x32_bf16 v[88:91], v[198:201], v[148:151], v[88:91]
	v_mfma_f32_16x16x32_bf16 v[84:87], v[190:193], v[166:169], v[84:87]
	v_mfma_f32_16x16x32_bf16 v[80:83], v[198:201], v[166:169], v[80:83]
	v_mfma_f32_16x16x32_bf16 v[76:79], v[190:193], v[174:177], v[76:79]
	v_mfma_f32_16x16x32_bf16 v[72:75], v[198:201], v[174:177], v[72:75]
	v_mfma_f32_16x16x32_bf16 v[68:71], v[190:193], v[182:185], v[68:71]
	s_setprio 0
	v_mfma_f32_16x16x32_bf16 v[64:67], v[198:201], v[182:185], v[64:67]
	s_barrier
	ds_read_b128 v[144:147], v209 offset:49152
	ds_read_b128 v[148:151], v209 offset:50176
	ds_read_b128 v[162:165], v209 offset:51200
	ds_read_b128 v[166:169], v209 offset:52224
	ds_read_b128 v[170:173], v209 offset:53248
	ds_read_b128 v[174:177], v209 offset:54272
	ds_read_b128 v[178:181], v209 offset:55296
	ds_read_b128 v[182:185], v209 offset:56320
	global_load_lds_dwordx4 v[202:203], off
	s_mov_b32 m0, s39
	v_lshl_add_u64 v[202:203], s[22:23], 0, v[156:157]
	global_load_lds_dwordx4 v[202:203], off
	s_barrier
	s_waitcnt lgkmcnt(0)
	s_setprio 1
	v_mfma_f32_16x16x32_bf16 v[60:63], v[128:131], v[144:147], v[60:63]
	v_mfma_f32_16x16x32_bf16 v[56:59], v[136:139], v[144:147], v[56:59]
	v_mfma_f32_16x16x32_bf16 v[52:55], v[128:131], v[162:165], v[52:55]
	v_mfma_f32_16x16x32_bf16 v[48:51], v[136:139], v[162:165], v[48:51]
	v_mfma_f32_16x16x32_bf16 v[44:47], v[128:131], v[170:173], v[44:47]
	v_mfma_f32_16x16x32_bf16 v[40:43], v[136:139], v[170:173], v[40:43]
	v_mfma_f32_16x16x32_bf16 v[36:39], v[128:131], v[178:181], v[36:39]
	v_mfma_f32_16x16x32_bf16 v[32:35], v[136:139], v[178:181], v[32:35]
	v_mfma_f32_16x16x32_bf16 v[60:63], v[132:135], v[148:151], v[60:63]
	v_mfma_f32_16x16x32_bf16 v[56:59], v[140:143], v[148:151], v[56:59]
	v_mfma_f32_16x16x32_bf16 v[52:55], v[132:135], v[166:169], v[52:55]
	v_mfma_f32_16x16x32_bf16 v[48:51], v[140:143], v[166:169], v[48:51]
	v_mfma_f32_16x16x32_bf16 v[44:47], v[132:135], v[174:177], v[44:47]
	v_mfma_f32_16x16x32_bf16 v[40:43], v[140:143], v[174:177], v[40:43]
	v_mfma_f32_16x16x32_bf16 v[36:39], v[132:135], v[182:185], v[36:39]
	s_setprio 0
	v_mfma_f32_16x16x32_bf16 v[32:35], v[140:143], v[182:185], v[32:35]
	s_barrier
	s_add_u32 s22, s24, s52
	s_addc_u32 s23, s25, 0
	s_add_i32 s24, s26, s31
	s_mov_b32 m0, s24
	v_lshl_add_u64 v[128:129], s[22:23], 0, v[152:153]
	global_load_lds_dwordx4 v[128:129], off
	s_add_i32 m0, s24, 0x2000
	v_lshl_add_u64 v[128:129], s[22:23], 0, v[156:157]
	global_load_lds_dwordx4 v[128:129], off
	s_waitcnt vmcnt(6)
	s_barrier
	s_setprio 1
	v_mfma_f32_16x16x32_bf16 v[28:31], v[186:189], v[144:147], v[28:31]
	v_mfma_f32_16x16x32_bf16 v[24:27], v[194:197], v[144:147], v[24:27]
	s_add_u32 s4, s4, 0x8000
	s_addc_u32 s5, s5, 0
	s_add_u32 s50, s50, 0x8000
	s_addc_u32 s51, s51, 0
	v_mfma_f32_16x16x32_bf16 v[20:23], v[186:189], v[162:165], v[20:23]
	v_mfma_f32_16x16x32_bf16 v[16:19], v[194:197], v[162:165], v[16:19]
	v_mfma_f32_16x16x32_bf16 v[12:15], v[186:189], v[170:173], v[12:15]
	v_mfma_f32_16x16x32_bf16 v[8:11], v[194:197], v[170:173], v[8:11]
	v_mfma_f32_16x16x32_bf16 v[4:7], v[186:189], v[178:181], v[4:7]
	v_mfma_f32_16x16x32_bf16 v[0:3], v[194:197], v[178:181], v[0:3]
	v_mfma_f32_16x16x32_bf16 v[28:31], v[190:193], v[148:151], v[28:31]
	v_mfma_f32_16x16x32_bf16 v[24:27], v[198:201], v[148:151], v[24:27]
	v_mfma_f32_16x16x32_bf16 v[20:23], v[190:193], v[166:169], v[20:23]
	v_mfma_f32_16x16x32_bf16 v[16:19], v[198:201], v[166:169], v[16:19]
	v_mfma_f32_16x16x32_bf16 v[12:15], v[190:193], v[174:177], v[12:15]
	v_mfma_f32_16x16x32_bf16 v[8:11], v[198:201], v[174:177], v[8:11]
	v_mfma_f32_16x16x32_bf16 v[4:7], v[190:193], v[182:185], v[4:7]
	s_cmp_ge_u32 s54, s28
	s_mov_b32 s22, s54
	s_setprio 0
	v_mfma_f32_16x16x32_bf16 v[0:3], v[198:201], v[182:185], v[0:3]
	s_barrier
	s_cbranch_scc0 .LBB0_187
	s_lshl_b32 s22, s49, 8
	s_add_i32 s22, s22, s37
	v_or_b32_e32 v162, s22, v206
	v_lshlrev_b32_e32 v170, 1, v162
	v_cndmask_b32_e64 v128, 0, 1, s[12:13]
	v_mov_b32_e32 v182, 1.0
	v_mov_b32_e32 v184, 0
	v_cmp_ne_u32_e64 s[4:5], 1, v128
	s_andn2_b64 vcc, exec, s[12:13]
	v_ashrrev_i32_e32 v171, 31, v170
	v_mov_b32_e32 v192, 0
	v_mov_b32_e32 v194, 1.0
	s_cbranch_vccnz .LBB0_190
	v_lshl_add_u64 v[128:129], v[170:171], 2, s[14:15]
	global_load_dwordx2 v[192:193], v[128:129], off
	s_waitcnt vmcnt(0)
	v_mov_b32_e32 v194, v193

; #define PG8_STAGE(bufoff, gbase, voff) do { _Pragma("unroll") for (int _i = 0; _i < 2; ++_i) \
;         __builtin_amdgcn_global_load_lds((const unsigned*)((const char*)(gbase) + (voff)[_i]), (LAS unsigned*)(lds + (bufoff) + ldsw + _i * 8192), 16, 0, 0); } while (0)
; #define PG8_LDA(dst, b, h) do { _Pragma("unroll") for (int m = 0; m < 4; ++m) _Pragma("unroll") for (int k = 0; k < 2; ++k) dst[m][k] = *(const LAS bf16x8*)(lds + PG8_SA(b, h) + aoff + m * 2048 + k * 1024); } while (0)
; #define PG8_LDB(dst, b, h) do { _Pragma("unroll") for (int n = 0; n < 2; ++n) _Pragma("unroll") for (int k = 0; k < 2; ++k) dst[n][k] = *(const LAS bf16x8*)(lds + PG8_SB(b, h) + boff + n * 2048 + k * 1024); } while (0)
; #define PG8_MMA(ai, bj, At, Bt) do { __builtin_amdgcn_s_setprio(1); _Pragma("unroll") for (int m = 0; m < 4; ++m) _Pragma("unroll") for (int n = 0; n < 2; ++n) _Pragma("unroll") for (int k = 0; k < 2; ++k) \
;         acc[ai][bj][m][n] = __builtin_amdgcn_mfma_f32_16x16x32_bf16(Bt[n][k], At[m][k], acc[ai][bj][m][n], 0, 0, 0); __builtin_amdgcn_s_setprio(0); } while (0)
; #define PG8_WAIT_L(n) asm volatile("s_waitcnt lgkmcnt(" #n ")" ::: "memory")
; #define PG8_BAR __builtin_amdgcn_s_barrier()
; #define PG8_SCHED __builtin_amdgcn_sched_barrier(0)
; template <class Epi>
; __device__ __forceinline__ void gemm_phase(LAS unsigned char* lds, const Gemm g, const StaticOrder& S, const Epi& E) {
;     ...
;             const bool last = (t == nt - 2);
;             const char* a1 = cA + (size_t)(t + 1) * kstep;
;             const char* a2 = last ? nA : cA + (size_t)(t + 2) * kstep; const char* b2 = last ? nB : cB + (size_t)(t + 2) * kstep;
;             const char* a3 = a2 + kstep; const char* b3 = b2 + kstep;
;             PG8_LDB(B0, 0, 0); PG8_SCHED; PG8_LDA(At, 0, 0); PG8_STAGE(PG8_SA(1, 1), a1 + hstepA, voffA);
;             PG8_WAIT_L(8); PG8_BAR; PG8_WAIT_L(0); PG8_MMA(0, 0, At, B0); PG8_BAR; PG8_SCHED;
;             PG8_LDB(B1, 0, 1); PG8_STAGE(PG8_SB(0, 0), b2, voffB);
;             PG8_BAR; PG8_WAIT_L(0); PG8_MMA(0, 1, At, B1); PG8_BAR;
;             PG8_LDA(At, 0, 1); PG8_STAGE(PG8_SA(0, 0), a2, voffA);
;             PG8_BAR; PG8_WAIT_L(0); PG8_MMA(1, 0, At, B0); PG8_BAR; PG8_SCHED;
.LBB0_247:
	s_mov_b32 s39, 0x10000
	v_add_u32_e32 v140, s39, v170
	ds_read_b128 v[128:131], v140
	ds_read_b128 v[132:135], v140 offset:1024
	ds_read_b128 v[136:139], v140 offset:2048
	ds_read_b128 v[140:143], v140 offset:3072
	ds_read_b128 v[144:147], v172
	ds_read_b128 v[148:151], v172 offset:1024
	ds_read_b128 v[166:169], v172 offset:2048
	ds_read_b128 v[174:177], v172 offset:3072
	ds_read_b128 v[178:181], v172 offset:4096
	ds_read_b128 v[182:185], v172 offset:5120
	ds_read_b128 v[186:189], v172 offset:6144
	ds_read_b128 v[190:193], v172 offset:7168
	s_add_u32 s14, s12, 0xfff84000
	s_addc_u32 s15, s13, -1
	s_cmp_eq_u32 s38, 28
	s_cselect_b32 s18, s11, s14
	s_cselect_b32 s19, s5, s15
	s_cselect_b32 s14, s35, s36
	s_cselect_b32 s15, s3, s37
	s_add_u32 s16, s18, 0x4000
	s_addc_u32 s17, s19, 0
	s_add_i32 m0, s25, 0xc000
	v_lshl_add_u64 v[194:195], s[12:13], 0, v[156:157]
	global_load_lds_dwordx4 v[194:195], off
	s_add_i32 m0, s25, 0xe000
	v_lshl_add_u64 v[194:195], s[12:13], 0, v[158:159]
	global_load_lds_dwordx4 v[194:195], off
	s_waitcnt lgkmcnt(8)
	s_barrier
	s_waitcnt lgkmcnt(0)
	s_setprio 1
	v_mfma_f32_16x16x32_bf16 v[124:127], v[128:131], v[144:147], v[124:127]
	v_mfma_f32_16x16x32_bf16 v[120:123], v[136:139], v[144:147], v[120:123]
	v_mfma_f32_16x16x32_bf16 v[108:111], v[128:131], v[166:169], v[108:111]
	v_mfma_f32_16x16x32_bf16 v[104:107], v[136:139], v[166:169], v[104:107]
	v_mfma_f32_16x16x32_bf16 v[92:95], v[128:131], v[178:181], v[92:95]
	v_mfma_f32_16x16x32_bf16 v[88:91], v[136:139], v[178:181], v[88:91]
	v_mfma_f32_16x16x32_bf16 v[76:79], v[128:131], v[186:189], v[76:79]
	v_mfma_f32_16x16x32_bf16 v[72:75], v[136:139], v[186:189], v[72:75]
	v_mfma_f32_16x16x32_bf16 v[124:127], v[132:135], v[148:151], v[124:127]
	v_mfma_f32_16x16x32_bf16 v[120:123], v[140:143], v[148:151], v[120:123]
	v_mfma_f32_16x16x32_bf16 v[108:111], v[132:135], v[174:177], v[108:111]
	v_mfma_f32_16x16x32_bf16 v[104:107], v[140:143], v[174:177], v[104:107]
	v_mfma_f32_16x16x32_bf16 v[92:95], v[132:135], v[182:185], v[92:95]
	v_mfma_f32_16x16x32_bf16 v[88:91], v[140:143], v[182:185], v[88:91]
	v_mfma_f32_16x16x32_bf16 v[76:79], v[132:135], v[190:193], v[76:79]
	s_setprio 0
	v_mfma_f32_16x16x32_bf16 v[72:75], v[140:143], v[190:193], v[72:75]
	s_barrier
	s_mov_b32 s42, 0x14000
	v_add_u32_e32 v152, s42, v170
	ds_read_b128 v[194:197], v152
	ds_read_b128 v[198:201], v152 offset:1024
	ds_read_b128 v[202:205], v152 offset:2048
	ds_read_b128 v[206:209], v152 offset:3072
	s_add_i32 s39, s39, s23
	s_mov_b32 m0, s39
	v_lshl_add_u64 v[210:211], s[14:15], 0, v[156:157]
	global_load_lds_dwordx4 v[210:211], off
	s_add_i32 m0, s39, 0x2000
	v_lshl_add_u64 v[210:211], s[14:15], 0, v[158:159]
	global_load_lds_dwordx4 v[210:211], off
	s_barrier
	s_waitcnt lgkmcnt(0)
	s_setprio 1
	v_mfma_f32_16x16x32_bf16 v[116:119], v[194:197], v[144:147], v[116:119]
	v_mfma_f32_16x16x32_bf16 v[112:115], v[202:205], v[144:147], v[112:115]
	s_mov_b32 m0, s25
	v_lshl_add_u64 v[210:211], s[18:19], 0, v[156:157]
	v_mfma_f32_16x16x32_bf16 v[100:103], v[194:197], v[166:169], v[100:103]
	v_mfma_f32_16x16x32_bf16 v[96:99], v[202:205], v[166:169], v[96:99]
	v_mfma_f32_16x16x32_bf16 v[84:87], v[194:197], v[178:181], v[84:87]
	v_mfma_f32_16x16x32_bf16 v[80:83], v[202:205], v[178:181], v[80:83]
	v_mfma_f32_16x16x32_bf16 v[68:71], v[194:197], v[186:189], v[68:71]
	v_mfma_f32_16x16x32_bf16 v[64:67], v[202:205], v[186:189], v[64:67]
	v_mfma_f32_16x16x32_bf16 v[116:119], v[198:201], v[148:151], v[116:119]
	v_mfma_f32_16x16x32_bf16 v[112:115], v[206:209], v[148:151], v[112:115]
	v_mfma_f32_16x16x32_bf16 v[100:103], v[198:201], v[174:177], v[100:103]
	v_mfma_f32_16x16x32_bf16 v[96:99], v[206:209], v[174:177], v[96:99]
	v_mfma_f32_16x16x32_bf16 v[84:87], v[198:201], v[182:185], v[84:87]
	v_mfma_f32_16x16x32_bf16 v[80:83], v[206:209], v[182:185], v[80:83]
	v_mfma_f32_16x16x32_bf16 v[68:71], v[198:201], v[190:193], v[68:71]
	s_setprio 0
	v_mfma_f32_16x16x32_bf16 v[64:67], v[206:209], v[190:193], v[64:67]
	s_barrier
	ds_read_b128 v[144:147], v172 offset:16384
	ds_read_b128 v[148:151], v172 offset:17408
	ds_read_b128 v[166:169], v172 offset:18432
	ds_read_b128 v[174:177], v172 offset:19456
	ds_read_b128 v[178:181], v172 offset:20480
	ds_read_b128 v[182:185], v172 offset:21504
	ds_read_b128 v[186:189], v172 offset:22528
	ds_read_b128 v[190:193], v172 offset:23552
	global_load_lds_dwordx4 v[210:211], off
	s_mov_b32 m0, s26
	v_lshl_add_u64 v[210:211], s[18:19], 0, v[158:159]
	global_load_lds_dwordx4 v[210:211], off
	s_barrier
	s_waitcnt lgkmcnt(0)
	s_setprio 1
	v_mfma_f32_16x16x32_bf16 v[60:63], v[128:131], v[144:147], v[60:63]
	v_mfma_f32_16x16x32_bf16 v[56:59], v[136:139], v[144:147], v[56:59]
	v_mfma_f32_16x16x32_bf16 v[44:47], v[128:131], v[166:169], v[44:47]
	v_mfma_f32_16x16x32_bf16 v[40:43], v[136:139], v[166:169], v[40:43]
	v_mfma_f32_16x16x32_bf16 v[28:31], v[128:131], v[178:181], v[28:31]
	v_mfma_f32_16x16x32_bf16 v[24:27], v[136:139], v[178:181], v[24:27]
	v_mfma_f32_16x16x32_bf16 v[12:15], v[128:131], v[186:189], v[12:15]
	v_mfma_f32_16x16x32_bf16 v[8:11], v[136:139], v[186:189], v[8:11]
	v_mfma_f32_16x16x32_bf16 v[60:63], v[132:135], v[148:151], v[60:63]
	v_mfma_f32_16x16x32_bf16 v[56:59], v[140:143], v[148:151], v[56:59]
	v_mfma_f32_16x16x32_bf16 v[44:47], v[132:135], v[174:177], v[44:47]
	v_mfma_f32_16x16x32_bf16 v[40:43], v[140:143], v[174:177], v[40:43]
	v_mfma_f32_16x16x32_bf16 v[28:31], v[132:135], v[182:185], v[28:31]
	v_mfma_f32_16x16x32_bf16 v[24:27], v[140:143], v[182:185], v[24:27]
	v_mfma_f32_16x16x32_bf16 v[12:15], v[132:135], v[190:193], v[12:15]
	s_setprio 0
	v_mfma_f32_16x16x32_bf16 v[8:11], v[140:143], v[190:193], v[8:11]
	s_barrier
; #define PG8_STAGE(bufoff, gbase, voff) do { _Pragma("unroll") for (int _i = 0; _i < 2; ++_i) \
;         __builtin_amdgcn_global_load_lds((const unsigned*)((const char*)(gbase) + (voff)[_i]), (LAS unsigned*)(lds + (bufoff) + ldsw + _i * 8192), 16, 0, 0); } while (0)
; #define PG8_LDA(dst, b, h) do { _Pragma("unroll") for (int m = 0; m < 4; ++m) _Pragma("unroll") for (int k = 0; k < 2; ++k) dst[m][k] = *(const LAS bf16x8*)(lds + PG8_SA(b, h) + aoff + m * 2048 + k * 1024); } while (0)
; #define PG8_LDB(dst, b, h) do { _Pragma("unroll") for (int n = 0; n < 2; ++n) _Pragma("unroll") for (int k = 0; k < 2; ++k) dst[n][k] = *(const LAS bf16x8*)(lds + PG8_SB(b, h) + boff + n * 2048 + k * 1024); } while (0)
; #define PG8_MMA(ai, bj, At, Bt) do { __builtin_amdgcn_s_setprio(1); _Pragma("unroll") for (int m = 0; m < 4; ++m) _Pragma("unroll") for (int n = 0; n < 2; ++n) _Pragma("unroll") for (int k = 0; k < 2; ++k) \
;         acc[ai][bj][m][n] = __builtin_amdgcn_mfma_f32_16x16x32_bf16(Bt[n][k], At[m][k], acc[ai][bj][m][n], 0, 0, 0); __builtin_amdgcn_s_setprio(0); } while (0)
; #define PG8_WAIT_V(n) asm volatile("s_waitcnt vmcnt(" #n ")" ::: "memory")
; #define PG8_WAIT_L(n) asm volatile("s_waitcnt lgkmcnt(" #n ")" ::: "memory")
; #define PG8_BAR __builtin_amdgcn_s_barrier()
; #define PG8_SCHED __builtin_amdgcn_sched_barrier(0)
; template <class Epi>
; __device__ __forceinline__ void gemm_phase(LAS unsigned char* lds, const Gemm g, const StaticOrder& S, const Epi& E) {
;     ...
;             PG8_STAGE(PG8_SB(0, 1), b2 + hstepB, voffB);
;             PG8_WAIT_V(6); PG8_BAR; PG8_MMA(1, 1, At, B1); PG8_BAR;
;             PG8_LDB(B0, 1, 0); PG8_SCHED; PG8_LDA(At, 1, 0); PG8_STAGE(PG8_SA(0, 1), a2 + hstepA, voffA);
;             PG8_WAIT_L(8); PG8_BAR; PG8_WAIT_L(0); PG8_MMA(0, 0, At, B0); PG8_BAR; PG8_SCHED;
;             PG8_LDB(B1, 1, 1); PG8_STAGE(PG8_SB(1, 0), b3, voffB);
;             PG8_BAR; PG8_WAIT_L(0); PG8_MMA(0, 1, At, B1); PG8_BAR;
;             PG8_LDA(At, 1, 1); PG8_STAGE(PG8_SA(1, 0), a3, voffA);
	s_add_u32 s40, s14, 0x80000
	s_addc_u32 s41, s15, 0
	s_add_i32 s39, s42, s23
	s_mov_b32 m0, s39
	v_lshl_add_u64 v[128:129], s[40:41], 0, v[156:157]
	global_load_lds_dwordx4 v[128:129], off
	s_add_i32 m0, s39, 0x2000
	v_lshl_add_u64 v[128:129], s[40:41], 0, v[158:159]
	global_load_lds_dwordx4 v[128:129], off
	s_waitcnt vmcnt(6)
	s_barrier
	s_setprio 1
	v_mfma_f32_16x16x32_bf16 v[52:55], v[194:197], v[144:147], v[52:55]
	v_mfma_f32_16x16x32_bf16 v[48:51], v[202:205], v[144:147], v[48:51]
	s_add_i32 s39, 0, 0x18000
	v_add_u32_e32 v140, s39, v170
	v_mfma_f32_16x16x32_bf16 v[36:39], v[194:197], v[166:169], v[36:39]
	v_mfma_f32_16x16x32_bf16 v[32:35], v[202:205], v[166:169], v[32:35]
	v_mfma_f32_16x16x32_bf16 v[20:23], v[194:197], v[178:181], v[20:23]
	v_mfma_f32_16x16x32_bf16 v[16:19], v[202:205], v[178:181], v[16:19]
	v_mfma_f32_16x16x32_bf16 v[4:7], v[194:197], v[186:189], v[4:7]
	v_mfma_f32_16x16x32_bf16 v[0:3], v[202:205], v[186:189], v[0:3]
	v_mfma_f32_16x16x32_bf16 v[52:55], v[198:201], v[148:151], v[52:55]
	v_mfma_f32_16x16x32_bf16 v[48:51], v[206:209], v[148:151], v[48:51]
	v_mfma_f32_16x16x32_bf16 v[36:39], v[198:201], v[174:177], v[36:39]
	v_mfma_f32_16x16x32_bf16 v[32:35], v[206:209], v[174:177], v[32:35]
	v_mfma_f32_16x16x32_bf16 v[20:23], v[198:201], v[182:185], v[20:23]
	v_mfma_f32_16x16x32_bf16 v[16:19], v[206:209], v[182:185], v[16:19]
	v_mfma_f32_16x16x32_bf16 v[4:7], v[198:201], v[190:193], v[4:7]
	s_setprio 0
	v_mfma_f32_16x16x32_bf16 v[0:3], v[206:209], v[190:193], v[0:3]
	s_barrier
	ds_read_b128 v[128:131], v140
	ds_read_b128 v[132:135], v140 offset:1024
	ds_read_b128 v[136:139], v140 offset:2048
	ds_read_b128 v[140:143], v140 offset:3072
	ds_read_b128 v[144:147], v172 offset:32768
	ds_read_b128 v[148:151], v172 offset:33792
	ds_read_b128 v[166:169], v172 offset:34816
	ds_read_b128 v[174:177], v172 offset:35840
	ds_read_b128 v[178:181], v172 offset:36864
	ds_read_b128 v[182:185], v172 offset:37888
	ds_read_b128 v[186:189], v172 offset:38912
	ds_read_b128 v[190:193], v172 offset:39936
	s_add_u32 s18, s18, 0x80000
	s_addc_u32 s19, s19, 0
	s_mov_b32 m0, s27
	v_lshl_add_u64 v[194:195], s[18:19], 0, v[156:157]
	global_load_lds_dwordx4 v[194:195], off
	s_mov_b32 m0, s28
	v_lshl_add_u64 v[194:195], s[18:19], 0, v[158:159]
	global_load_lds_dwordx4 v[194:195], off
	s_waitcnt lgkmcnt(8)
	s_barrier
	s_waitcnt lgkmcnt(0)
	s_setprio 1
	v_mfma_f32_16x16x32_bf16 v[124:127], v[128:131], v[144:147], v[124:127]
	v_mfma_f32_16x16x32_bf16 v[120:123], v[136:139], v[144:147], v[120:123]
	v_mfma_f32_16x16x32_bf16 v[108:111], v[128:131], v[166:169], v[108:111]
	v_mfma_f32_16x16x32_bf16 v[104:107], v[136:139], v[166:169], v[104:107]
	v_mfma_f32_16x16x32_bf16 v[92:95], v[128:131], v[178:181], v[92:95]
	v_mfma_f32_16x16x32_bf16 v[88:91], v[136:139], v[178:181], v[88:91]
	v_mfma_f32_16x16x32_bf16 v[76:79], v[128:131], v[186:189], v[76:79]
	v_mfma_f32_16x16x32_bf16 v[72:75], v[136:139], v[186:189], v[72:75]
	v_mfma_f32_16x16x32_bf16 v[124:127], v[132:135], v[148:151], v[124:127]
	v_mfma_f32_16x16x32_bf16 v[120:123], v[140:143], v[148:151], v[120:123]
	v_mfma_f32_16x16x32_bf16 v[108:111], v[132:135], v[174:177], v[108:111]
	v_mfma_f32_16x16x32_bf16 v[104:107], v[140:143], v[174:177], v[104:107]
	v_mfma_f32_16x16x32_bf16 v[92:95], v[132:135], v[182:185], v[92:95]
	v_mfma_f32_16x16x32_bf16 v[88:91], v[140:143], v[182:185], v[88:91]
	v_mfma_f32_16x16x32_bf16 v[76:79], v[132:135], v[190:193], v[76:79]
	s_setprio 0
	v_mfma_f32_16x16x32_bf16 v[72:75], v[140:143], v[190:193], v[72:75]
	s_barrier
	s_mov_b32 s40, 0x1c000
	v_add_u32_e32 v152, s40, v170
	ds_read_b128 v[194:197], v152
	ds_read_b128 v[198:201], v152 offset:1024
	ds_read_b128 v[202:205], v152 offset:2048
	ds_read_b128 v[206:209], v152 offset:3072
	s_add_u32 s18, s14, 0x4000
	s_addc_u32 s19, s15, 0
	s_add_i32 s39, s39, s23
	s_mov_b32 m0, s39
	v_lshl_add_u64 v[210:211], s[18:19], 0, v[156:157]
	global_load_lds_dwordx4 v[210:211], off
	s_add_i32 m0, s39, 0x2000
	v_lshl_add_u64 v[210:211], s[18:19], 0, v[158:159]
	global_load_lds_dwordx4 v[210:211], off
	s_barrier
	s_waitcnt lgkmcnt(0)
	s_setprio 1
	v_mfma_f32_16x16x32_bf16 v[116:119], v[194:197], v[144:147], v[116:119]
	v_mfma_f32_16x16x32_bf16 v[112:115], v[202:205], v[144:147], v[112:115]
	s_mov_b32 m0, s29
	v_lshl_add_u64 v[210:211], s[16:17], 0, v[156:157]
	v_mfma_f32_16x16x32_bf16 v[100:103], v[194:197], v[166:169], v[100:103]
	v_mfma_f32_16x16x32_bf16 v[96:99], v[202:205], v[166:169], v[96:99]
	v_mfma_f32_16x16x32_bf16 v[84:87], v[194:197], v[178:181], v[84:87]
	v_mfma_f32_16x16x32_bf16 v[80:83], v[202:205], v[178:181], v[80:83]
	v_mfma_f32_16x16x32_bf16 v[68:71], v[194:197], v[186:189], v[68:71]
	v_mfma_f32_16x16x32_bf16 v[64:67], v[202:205], v[186:189], v[64:67]
	v_mfma_f32_16x16x32_bf16 v[116:119], v[198:201], v[148:151], v[116:119]
	v_mfma_f32_16x16x32_bf16 v[112:115], v[206:209], v[148:151], v[112:115]
	v_mfma_f32_16x16x32_bf16 v[100:103], v[198:201], v[174:177], v[100:103]
	v_mfma_f32_16x16x32_bf16 v[96:99], v[206:209], v[174:177], v[96:99]
	v_mfma_f32_16x16x32_bf16 v[84:87], v[198:201], v[182:185], v[84:87]
	v_mfma_f32_16x16x32_bf16 v[80:83], v[206:209], v[182:185], v[80:83]
	v_mfma_f32_16x16x32_bf16 v[68:71], v[198:201], v[190:193], v[68:71]
	s_setprio 0
	v_mfma_f32_16x16x32_bf16 v[64:67], v[206:209], v[190:193], v[64:67]
	s_barrier
	ds_read_b128 v[144:147], v172 offset:49152
	ds_read_b128 v[148:151], v172 offset:50176
	ds_read_b128 v[166:169], v172 offset:51200
	ds_read_b128 v[174:177], v172 offset:52224
	ds_read_b128 v[178:181], v172 offset:53248
	ds_read_b128 v[182:185], v172 offset:54272
	ds_read_b128 v[186:189], v172 offset:55296
	ds_read_b128 v[190:193], v172 offset:56320
	global_load_lds_dwordx4 v[210:211], off
	s_mov_b32 m0, s30
	v_lshl_add_u64 v[210:211], s[16:17], 0, v[158:159]
	global_load_lds_dwordx4 v[210:211], off
	s_barrier
; #define PG8_STAGE(bufoff, gbase, voff) do { _Pragma("unroll") for (int _i = 0; _i < 2; ++_i) \
;         __builtin_amdgcn_global_load_lds((const unsigned*)((const char*)(gbase) + (voff)[_i]), (LAS unsigned*)(lds + (bufoff) + ldsw + _i * 8192), 16, 0, 0); } while (0)
; #define PG8_MMA(ai, bj, At, Bt) do { __builtin_amdgcn_s_setprio(1); _Pragma("unroll") for (int m = 0; m < 4; ++m) _Pragma("unroll") for (int n = 0; n < 2; ++n) _Pragma("unroll") for (int k = 0; k < 2; ++k) \
;         acc[ai][bj][m][n] = __builtin_amdgcn_mfma_f32_16x16x32_bf16(Bt[n][k], At[m][k], acc[ai][bj][m][n], 0, 0, 0); __builtin_amdgcn_s_setprio(0); } while (0)
; #define PG8_WAIT_V(n) asm volatile("s_waitcnt vmcnt(" #n ")" ::: "memory")
; #define PG8_WAIT_L(n) asm volatile("s_waitcnt lgkmcnt(" #n ")" ::: "memory")
; #define PG8_BAR __builtin_amdgcn_s_barrier()
; #define PG8_SCHED __builtin_amdgcn_sched_barrier(0)
; template <class Epi>
; __device__ __forceinline__ void gemm_phase(LAS unsigned char* lds, const Gemm g, const StaticOrder& S, const Epi& E) {
;     ...
;             PG8_BAR; PG8_WAIT_L(0); PG8_MMA(1, 0, At, B0); PG8_BAR; PG8_SCHED;
;             PG8_STAGE(PG8_SB(1, 1), b3 + hstepB, voffB);
;             PG8_WAIT_V(6); PG8_BAR; PG8_MMA(1, 1, At, B1); PG8_BAR;
;     __device__ __forceinline__ void operator()(const f32x4 (&acc)[2][2][4][2], const Unit& u, int wr, int wc, int fr, int fq) const {
;         const int row0 = u.pm * BM + wr * 64 + fr, j0 = wc * 16 + 4 * fq, colb = u.pn * BM + j0;
;         if (u.pn < 8) {
	s_waitcnt lgkmcnt(0)
	s_setprio 1
	v_mfma_f32_16x16x32_bf16 v[60:63], v[128:131], v[144:147], v[60:63]
	v_mfma_f32_16x16x32_bf16 v[56:59], v[136:139], v[144:147], v[56:59]
	v_mfma_f32_16x16x32_bf16 v[44:47], v[128:131], v[166:169], v[44:47]
	v_mfma_f32_16x16x32_bf16 v[40:43], v[136:139], v[166:169], v[40:43]
	v_mfma_f32_16x16x32_bf16 v[28:31], v[128:131], v[178:181], v[28:31]
	v_mfma_f32_16x16x32_bf16 v[24:27], v[136:139], v[178:181], v[24:27]
	v_mfma_f32_16x16x32_bf16 v[12:15], v[128:131], v[186:189], v[12:15]
	v_mfma_f32_16x16x32_bf16 v[8:11], v[136:139], v[186:189], v[8:11]
	v_mfma_f32_16x16x32_bf16 v[60:63], v[132:135], v[148:151], v[60:63]
	v_mfma_f32_16x16x32_bf16 v[56:59], v[140:143], v[148:151], v[56:59]
	v_mfma_f32_16x16x32_bf16 v[44:47], v[132:135], v[174:177], v[44:47]
	v_mfma_f32_16x16x32_bf16 v[40:43], v[140:143], v[174:177], v[40:43]
	v_mfma_f32_16x16x32_bf16 v[28:31], v[132:135], v[182:185], v[28:31]
	v_mfma_f32_16x16x32_bf16 v[24:27], v[140:143], v[182:185], v[24:27]
	v_mfma_f32_16x16x32_bf16 v[12:15], v[132:135], v[190:193], v[12:15]
	s_setprio 0
	v_mfma_f32_16x16x32_bf16 v[8:11], v[140:143], v[190:193], v[8:11]
	s_barrier
	s_add_u32 s14, s14, 0x84000
	s_addc_u32 s15, s15, 0
	s_add_i32 s16, s40, s23
	s_mov_b32 m0, s16
	v_lshl_add_u64 v[128:129], s[14:15], 0, v[156:157]
	global_load_lds_dwordx4 v[128:129], off
	s_add_i32 m0, s16, 0x2000
	v_lshl_add_u64 v[128:129], s[14:15], 0, v[158:159]
	global_load_lds_dwordx4 v[128:129], off
	s_waitcnt vmcnt(6)
	s_barrier
	s_setprio 1
	v_mfma_f32_16x16x32_bf16 v[52:55], v[194:197], v[144:147], v[52:55]
	v_mfma_f32_16x16x32_bf16 v[48:51], v[202:205], v[144:147], v[48:51]
	s_add_i32 s38, s38, 2
	s_add_u32 s12, s12, 0x8000
	s_addc_u32 s13, s13, 0
	s_add_u32 s36, s36, 0x8000
	s_addc_u32 s37, s37, 0
	v_mfma_f32_16x16x32_bf16 v[36:39], v[194:197], v[166:169], v[36:39]
	v_mfma_f32_16x16x32_bf16 v[32:35], v[202:205], v[166:169], v[32:35]
	v_mfma_f32_16x16x32_bf16 v[20:23], v[194:197], v[178:181], v[20:23]
	v_mfma_f32_16x16x32_bf16 v[16:19], v[202:205], v[178:181], v[16:19]
	v_mfma_f32_16x16x32_bf16 v[4:7], v[194:197], v[186:189], v[4:7]
	v_mfma_f32_16x16x32_bf16 v[0:3], v[202:205], v[186:189], v[0:3]
	v_mfma_f32_16x16x32_bf16 v[52:55], v[198:201], v[148:151], v[52:55]
	v_mfma_f32_16x16x32_bf16 v[48:51], v[206:209], v[148:151], v[48:51]
	v_mfma_f32_16x16x32_bf16 v[36:39], v[198:201], v[174:177], v[36:39]
	v_mfma_f32_16x16x32_bf16 v[32:35], v[206:209], v[174:177], v[32:35]
	v_mfma_f32_16x16x32_bf16 v[20:23], v[198:201], v[182:185], v[20:23]
	v_mfma_f32_16x16x32_bf16 v[16:19], v[206:209], v[182:185], v[16:19]
	v_mfma_f32_16x16x32_bf16 v[4:7], v[198:201], v[190:193], v[4:7]
	s_cmp_gt_u32 s38, 29
	s_setprio 0
	v_mfma_f32_16x16x32_bf16 v[0:3], v[206:209], v[190:193], v[0:3]
	s_barrier
	s_cbranch_scc0 .LBB0_247
	v_lshl_add_u32 v177, s10, 8, v165
	v_lshl_or_b32 v152, s34, 8, v171
	s_mov_b64 s[10:11], -1
	s_cmp_lt_i32 s34, 8
	v_or_b32_e32 v180, 16, v177
	v_or_b32_e32 v179, 32, v177
	v_or_b32_e32 v178, 48, v177
	v_add_u32_e32 v176, 0x80, v177
	v_add_u32_e32 v175, 0x90, v177
	v_add_u32_e32 v174, 0xa0, v177
	v_add_u32_e32 v173, 0xb0, v177
	s_cbranch_scc1 .LBB0_250
; __device__ __forceinline__ unsigned cvt_pk_bf16(float lo, float hi) { unsigned r; asm volatile("v_cvt_pk_bf16_f32 %0, %1, %2" : "=v"(r) : "v"(lo), "v"(hi)); return r; }
;     __device__ __forceinline__ void operator()(const f32x4 (&acc)[2][2][4][2], const Unit& u, int wr, int wc, int fr, int fq) const {
;     ...
; #pragma unroll
;             for (int ai = 0; ai < 2; ++ai)
; #pragma unroll
;                 for (int m = 0; m < 4; ++m) {
;                     const int row = row0 + ai * HALF + m * 16;
;                     bf16_t* rowp = O + (size_t)row * DIN + colb;
; #pragma unroll
;                     for (int bj = 0; bj < 2; ++bj) {
;                         const f32x4 o1 = acc[ai][bj][m][0], o2 = acc[ai][bj][m][1];
;                         u32x2 w1, w2; w1.x = cvt_pk_bf16(o1[0], o1[1]); w1.y = cvt_pk_bf16(o1[2], o1[3]); w2.x = cvt_pk_bf16(o2[0], o2[1]); w2.y = cvt_pk_bf16(o2[2], o2[3]);
;                         *(u32x2*)(rowp + bj * HALF) = w1; *(u32x2*)(rowp + bj * HALF + 64) = w2;
;                     }
;                 }
	v_readlane_b32 s10, v252, 57
	v_readlane_b32 s11, v252, 58
	s_movk_i32 s3, 0x3000
	v_lshlrev_b64 v[130:131], 1, v[152:153]
	v_mov_b64_e32 v[128:129], s[10:11]
	v_mad_i64_i32 v[132:133], s[10:11], v177, s3, v[128:129]
	v_lshl_add_u64 v[132:133], v[132:133], 0, v[130:131]
	v_cvt_pk_bf16_f32 v134, v124, v125
	v_cvt_pk_bf16_f32 v135, v126, v127
	v_cvt_pk_bf16_f32 v136, v120, v121
	v_cvt_pk_bf16_f32 v137, v122, v123
	global_store_dwordx2 v[132:133], v[134:135], off
	global_store_dwordx2 v[132:133], v[136:137], off offset:128
	v_cvt_pk_bf16_f32 v134, v116, v117
	v_cvt_pk_bf16_f32 v135, v118, v119
	v_cvt_pk_bf16_f32 v136, v112, v113
	v_cvt_pk_bf16_f32 v137, v114, v115
	global_store_dwordx2 v[132:133], v[134:135], off offset:256
	global_store_dwordx2 v[132:133], v[136:137], off offset:384
	v_mad_i64_i32 v[132:133], s[10:11], v180, s3, v[128:129]
	v_lshl_add_u64 v[132:133], v[132:133], 0, v[130:131]
	v_cvt_pk_bf16_f32 v134, v108, v109
	v_cvt_pk_bf16_f32 v135, v110, v111
	v_cvt_pk_bf16_f32 v136, v104, v105
	v_cvt_pk_bf16_f32 v137, v106, v107
	global_store_dwordx2 v[132:133], v[134:135], off
	global_store_dwordx2 v[132:133], v[136:137], off offset:128
	v_cvt_pk_bf16_f32 v134, v100, v101
	v_cvt_pk_bf16_f32 v135, v102, v103
	v_cvt_pk_bf16_f32 v136, v96, v97
	v_cvt_pk_bf16_f32 v137, v98, v99
	global_store_dwordx2 v[132:133], v[134:135], off offset:256
	global_store_dwordx2 v[132:133], v[136:137], off offset:384
	v_mad_i64_i32 v[132:133], s[10:11], v179, s3, v[128:129]
	v_lshl_add_u64 v[132:133], v[132:133], 0, v[130:131]
	v_cvt_pk_bf16_f32 v134, v92, v93
	v_cvt_pk_bf16_f32 v135, v94, v95
	v_cvt_pk_bf16_f32 v136, v88, v89
	v_cvt_pk_bf16_f32 v137, v90, v91
	global_store_dwordx2 v[132:133], v[134:135], off
	global_store_dwordx2 v[132:133], v[136:137], off offset:128
	v_cvt_pk_bf16_f32 v134, v84, v85
	v_cvt_pk_bf16_f32 v135, v86, v87
	v_cvt_pk_bf16_f32 v136, v80, v81
	v_cvt_pk_bf16_f32 v137, v82, v83
	global_store_dwordx2 v[132:133], v[134:135], off offset:256
	global_store_dwordx2 v[132:133], v[136:137], off offset:384
	v_mad_i64_i32 v[132:133], s[10:11], v178, s3, v[128:129]
	v_lshl_add_u64 v[132:133], v[132:133], 0, v[130:131]
	v_cvt_pk_bf16_f32 v134, v76, v77
	v_cvt_pk_bf16_f32 v135, v78, v79
	v_cvt_pk_bf16_f32 v136, v72, v73
	v_cvt_pk_bf16_f32 v137, v74, v75
	global_store_dwordx2 v[132:133], v[134:135], off
	global_store_dwordx2 v[132:133], v[136:137], off offset:128
	v_cvt_pk_bf16_f32 v134, v68, v69
	v_cvt_pk_bf16_f32 v135, v70, v71
	v_cvt_pk_bf16_f32 v136, v64, v65
	v_cvt_pk_bf16_f32 v137, v66, v67
	global_store_dwordx2 v[132:133], v[134:135], off offset:256
	global_store_dwordx2 v[132:133], v[136:137], off offset:384
	v_mad_i64_i32 v[132:133], s[10:11], v176, s3, v[128:129]
	v_lshl_add_u64 v[132:133], v[132:133], 0, v[130:131]
	v_cvt_pk_bf16_f32 v134, v60, v61
	v_cvt_pk_bf16_f32 v135, v62, v63
	v_cvt_pk_bf16_f32 v136, v56, v57
	v_cvt_pk_bf16_f32 v137, v58, v59
	global_store_dwordx2 v[132:133], v[134:135], off
	global_store_dwordx2 v[132:133], v[136:137], off offset:128
	v_cvt_pk_bf16_f32 v134, v52, v53
	v_cvt_pk_bf16_f32 v135, v54, v55
	v_cvt_pk_bf16_f32 v136, v48, v49
	v_cvt_pk_bf16_f32 v137, v50, v51
	global_store_dwordx2 v[132:133], v[134:135], off offset:256
	global_store_dwordx2 v[132:133], v[136:137], off offset:384
	v_mad_i64_i32 v[132:133], s[10:11], v175, s3, v[128:129]
	v_lshl_add_u64 v[132:133], v[132:133], 0, v[130:131]
	v_cvt_pk_bf16_f32 v134, v44, v45
	v_cvt_pk_bf16_f32 v135, v46, v47
	v_cvt_pk_bf16_f32 v136, v40, v41
	v_cvt_pk_bf16_f32 v137, v42, v43
	global_store_dwordx2 v[132:133], v[134:135], off
	global_store_dwordx2 v[132:133], v[136:137], off offset:128
	v_cvt_pk_bf16_f32 v134, v36, v37
	v_cvt_pk_bf16_f32 v135, v38, v39
	v_cvt_pk_bf16_f32 v136, v32, v33
	v_cvt_pk_bf16_f32 v137, v34, v35
	global_store_dwordx2 v[132:133], v[134:135], off offset:256
	global_store_dwordx2 v[132:133], v[136:137], off offset:384
	v_mad_i64_i32 v[132:133], s[10:11], v174, s3, v[128:129]
	v_lshl_add_u64 v[132:133], v[132:133], 0, v[130:131]
	v_cvt_pk_bf16_f32 v134, v28, v29
	v_cvt_pk_bf16_f32 v135, v30, v31
	v_cvt_pk_bf16_f32 v136, v24, v25
	v_cvt_pk_bf16_f32 v137, v26, v27
	global_store_dwordx2 v[132:133], v[134:135], off
	global_store_dwordx2 v[132:133], v[136:137], off offset:128
	v_cvt_pk_bf16_f32 v134, v20, v21
	v_cvt_pk_bf16_f32 v135, v22, v23
	v_mad_i64_i32 v[128:129], s[10:11], v173, s3, v[128:129]
	v_cvt_pk_bf16_f32 v136, v16, v17
	v_cvt_pk_bf16_f32 v137, v18, v19
	global_store_dwordx2 v[132:133], v[134:135], off offset:256
	global_store_dwordx2 v[132:133], v[136:137], off offset:384
	v_lshl_add_u64 v[128:129], v[128:129], 0, v[130:131]
	v_cvt_pk_bf16_f32 v130, v12, v13
	v_cvt_pk_bf16_f32 v131, v14, v15
	v_cvt_pk_bf16_f32 v132, v8, v9
	v_cvt_pk_bf16_f32 v133, v10, v11
	s_mov_b64 s[10:11], 0
	global_store_dwordx2 v[128:129], v[130:131], off
	global_store_dwordx2 v[128:129], v[132:133], off offset:128
	v_cvt_pk_bf16_f32 v130, v4, v5
	v_cvt_pk_bf16_f32 v131, v6, v7
	v_cvt_pk_bf16_f32 v132, v0, v1
	v_cvt_pk_bf16_f32 v133, v2, v3
